# grid barriers 5 and 6 replaced by 4-workgroup group syncs on per-row-panel counters plus two wide arrival counters; publishing stores made write-through (sc1)
# baseline (speedup 1.0000x reference)
_Z10fwd_kernel4Args:
	s_load_dwordx4 s[76:79], s[0:1], 0xa0
	s_load_dwordx8 s[84:91], s[0:1], 0x80
	s_mov_b32 s96, s2
	s_mov_b64 s[2:3], 0
	s_waitcnt lgkmcnt(0)
	v_mov_b32_e32 v244, s78
	v_mov_b32_e32 v245, s79
	v_add_co_u32_e32 v244, vcc, 0xefebe00, v244
	s_and_b32 s98, s96, 7
	s_lshl_b32 s98, s98, 3
	s_bfe_u32 s99, s96, 0x30003
	v_addc_co_u32_e32 v245, vcc, 0, v245, vcc
	s_add_i32 s98, s98, s99
	s_lshl_b32 s98, s98, 2
	v_writelane_b32 v243, s98, 0
	v_writelane_b32 v243, s96, 1
	s_cmp_eq_u64 s[78:79], 0
	s_cbranch_scc1 .LBB0_2
	v_and_b32_e32 v202, 0x3ff, v0
	s_andn2_b64 vcc, exec, s[2:3]
	s_cbranch_vccz .LBB0_3
	s_branch .LBB0_14

.LBB0_806:
	s_or_b64 exec, exec, s[8:9]
	s_waitcnt vmcnt(13)
	v_mfma_f32_16x16x32_bf16 v[0:3], v[8:11], v[0:3], 0
	s_waitcnt lgkmcnt(0)
	s_barrier
	s_waitcnt vmcnt(12)
	v_mfma_f32_16x16x32_bf16 v[0:3], v[12:15], v[4:7], v[0:3]
	s_waitcnt vmcnt(9)
	v_mfma_f32_16x16x32_bf16 v[0:3], v[24:27], v[16:19], v[0:3]
	s_waitcnt vmcnt(8)
	v_mfma_f32_16x16x32_bf16 v[0:3], v[28:31], v[20:23], v[0:3]
	s_waitcnt vmcnt(5)
	v_mfma_f32_16x16x32_bf16 v[0:3], v[48:51], v[32:35], v[0:3]
	s_waitcnt vmcnt(4)
	v_mfma_f32_16x16x32_bf16 v[0:3], v[52:55], v[40:43], v[0:3]
	s_waitcnt vmcnt(1)
	v_mfma_f32_16x16x32_bf16 v[0:3], v[60:63], v[56:59], v[0:3]
	s_waitcnt vmcnt(0)
	v_mfma_f32_16x16x32_bf16 v[0:3], v[44:47], v[36:39], v[0:3]
	s_nop 7
	ds_write_b128 v78, v[0:3]
	s_waitcnt lgkmcnt(0)
	s_barrier
	s_and_saveexec_b64 s[8:9], s[0:1]
	s_cbranch_execz .LBB0_803
	ds_read_b128 v[0:3], v78
	ds_read_b128 v[4:7], v79 offset:2048
	ds_read_b128 v[8:11], v79 offset:4096
	ds_read_b128 v[12:15], v79 offset:6144
	v_lshlrev_b32_e32 v16, 16, v74
	v_and_b32_e32 v17, 0xffff0000, v74
	v_lshlrev_b32_e32 v18, 16, v75
	v_and_b32_e32 v19, 0xffff0000, v75
	s_waitcnt lgkmcnt(2)
	v_pk_add_f32 v[2:3], v[2:3], v[6:7]
	v_pk_add_f32 v[0:1], v[0:1], v[4:5]
	s_waitcnt lgkmcnt(0)
	v_pk_add_f32 v[4:5], v[10:11], v[14:15]
	v_pk_add_f32 v[6:7], v[8:9], v[12:13]
	v_lshlrev_b32_e32 v24, 10, v71
	v_lshlrev_b32_e32 v20, 16, v72
	v_and_b32_e32 v21, 0xffff0000, v72
	v_lshlrev_b32_e32 v22, 16, v73
	v_and_b32_e32 v23, 0xffff0000, v73
	v_pk_fma_f32 v[2:3], v[2:3], v[18:19], v[4:5]
	v_pk_fma_f32 v[0:1], v[0:1], v[16:17], v[6:7]
	v_pk_mul_f32 v[2:3], v[2:3], v[22:23]
	v_pk_mul_f32 v[0:1], v[0:1], v[20:21]
	v_lshlrev_b32_e32 v64, 1, v24
	v_cvt_pk_bf16_f32 v0, v0, v1
	v_cvt_pk_bf16_f32 v1, v2, v3
	v_lshl_add_u64 v[2:3], s[4:5], 0, v[64:65]
	v_ashrrev_i32_e32 v71, 31, v70
	v_lshl_add_u64 v[2:3], v[70:71], 1, v[2:3]
	global_store_dwordx2 v[2:3], v[0:1], off sc1
	s_branch .LBB0_803

.LBB0_818:
	s_add_u32 s16, s2, s4
	ds_read_b128 v[84:87], v164
	ds_read_b128 v[136:139], v164 offset:1024
	ds_read_b128 v[140:143], v164 offset:2048
	ds_read_b128 v[144:147], v164 offset:3072
	s_addc_u32 s17, s3, s5
	s_add_u32 s16, s16, 0xcd48500
	s_addc_u32 s17, s17, 0
	s_add_u32 s26, s38, s4
	s_addc_u32 s27, s39, s5
	s_cmpk_eq_i32 s4, 0x300
	s_cselect_b32 s37, s15, s17
	s_cselect_b32 s36, s1, s16
	s_cselect_b32 s17, s33, s27
	s_cselect_b32 s16, s25, s26
	s_mov_b32 m0, s60
	v_lshl_add_u64 v[160:161], v[16:17], 0, s[4:5]
	ds_read_b128 v[156:159], v165
	ds_read_b128 v[170:173], v165 offset:1024
	ds_read_b128 v[174:177], v165 offset:2048
	ds_read_b128 v[178:181], v165 offset:3072
	ds_read_b128 v[182:185], v165 offset:4096
	ds_read_b128 v[186:189], v165 offset:5120
	ds_read_b128 v[190:193], v165 offset:6144
	ds_read_b128 v[194:197], v165 offset:7168
	global_load_lds_dwordx4 v[160:161], off
	v_lshl_add_u64 v[160:161], v[18:19], 0, s[4:5]
	s_mov_b32 m0, s61
	s_nop 0
	global_load_lds_dwordx4 v[160:161], off
	s_waitcnt lgkmcnt(8)
	s_barrier
	s_waitcnt lgkmcnt(0)
	s_setprio 1
	s_waitcnt lgkmcnt(0)
	v_mfma_f32_16x16x32_bf16 v[124:127], v[84:87], v[156:159], v[124:127]
	v_mfma_f32_16x16x32_bf16 v[120:123], v[140:143], v[156:159], v[120:123]
	v_mfma_f32_16x16x32_bf16 v[116:119], v[84:87], v[174:177], v[116:119]
	v_mfma_f32_16x16x32_bf16 v[112:115], v[140:143], v[174:177], v[112:115]
	v_mfma_f32_16x16x32_bf16 v[96:99], v[84:87], v[182:185], v[96:99]
	v_mfma_f32_16x16x32_bf16 v[100:103], v[140:143], v[182:185], v[100:103]
	v_mfma_f32_16x16x32_bf16 v[80:83], v[84:87], v[190:193], v[80:83]
	v_mfma_f32_16x16x32_bf16 v[76:79], v[140:143], v[190:193], v[76:79]
	v_mfma_f32_16x16x32_bf16 v[124:127], v[136:139], v[170:173], v[124:127]
	v_mfma_f32_16x16x32_bf16 v[120:123], v[144:147], v[170:173], v[120:123]
	v_mfma_f32_16x16x32_bf16 v[116:119], v[136:139], v[178:181], v[116:119]
	v_mfma_f32_16x16x32_bf16 v[112:115], v[144:147], v[178:181], v[112:115]
	v_mfma_f32_16x16x32_bf16 v[96:99], v[136:139], v[186:189], v[96:99]
	v_mfma_f32_16x16x32_bf16 v[100:103], v[144:147], v[186:189], v[100:103]
	v_mfma_f32_16x16x32_bf16 v[80:83], v[136:139], v[194:197], v[80:83]
	v_mfma_f32_16x16x32_bf16 v[76:79], v[144:147], v[194:197], v[76:79]
	s_setprio 0
	s_barrier
	s_mov_b32 m0, s62
	v_lshl_add_u64 v[160:161], s[16:17], 0, v[150:151]
	ds_read_b128 v[198:201], v166
	ds_read_b128 v[210:213], v166 offset:1024
	ds_read_b128 v[214:217], v166 offset:2048
	ds_read_b128 v[218:221], v166 offset:3072
	global_load_lds_dwordx4 v[160:161], off
	v_lshl_add_u64 v[222:223], s[16:17], 0, v[154:155]
	s_mov_b32 m0, s63
	s_nop 0
	global_load_lds_dwordx4 v[222:223], off
	s_barrier
	s_waitcnt lgkmcnt(0)
	s_setprio 1
	s_waitcnt lgkmcnt(0)
	v_mfma_f32_16x16x32_bf16 v[128:131], v[198:201], v[156:159], v[128:131]
	v_mfma_f32_16x16x32_bf16 v[132:135], v[214:217], v[156:159], v[132:135]
	v_mfma_f32_16x16x32_bf16 v[104:107], v[198:201], v[174:177], v[104:107]
	v_mfma_f32_16x16x32_bf16 v[108:111], v[214:217], v[174:177], v[108:111]
	v_mfma_f32_16x16x32_bf16 v[88:91], v[198:201], v[182:185], v[88:91]
	v_mfma_f32_16x16x32_bf16 v[92:95], v[214:217], v[182:185], v[92:95]
	v_mfma_f32_16x16x32_bf16 v[68:71], v[198:201], v[190:193], v[68:71]
	v_mfma_f32_16x16x32_bf16 v[72:75], v[214:217], v[190:193], v[72:75]
	v_mfma_f32_16x16x32_bf16 v[128:131], v[210:213], v[170:173], v[128:131]
	v_mfma_f32_16x16x32_bf16 v[132:135], v[218:221], v[170:173], v[132:135]
	v_mfma_f32_16x16x32_bf16 v[104:107], v[210:213], v[178:181], v[104:107]
	v_mfma_f32_16x16x32_bf16 v[108:111], v[218:221], v[178:181], v[108:111]
	v_mfma_f32_16x16x32_bf16 v[88:91], v[210:213], v[186:189], v[88:91]
	v_mfma_f32_16x16x32_bf16 v[92:95], v[218:221], v[186:189], v[92:95]
	v_mfma_f32_16x16x32_bf16 v[68:71], v[210:213], v[194:197], v[68:71]
	v_mfma_f32_16x16x32_bf16 v[72:75], v[218:221], v[194:197], v[72:75]
	s_setprio 0
	s_mov_b32 m0, s19
	v_lshl_add_u64 v[224:225], s[36:37], 0, v[148:149]
	s_barrier
	ds_read_b128 v[156:159], v165 offset:16384
	ds_read_b128 v[170:173], v165 offset:17408
	ds_read_b128 v[174:177], v165 offset:18432
	ds_read_b128 v[178:181], v165 offset:19456
	ds_read_b128 v[182:185], v165 offset:20480
	ds_read_b128 v[186:189], v165 offset:21504
	ds_read_b128 v[190:193], v165 offset:22528
	ds_read_b128 v[194:197], v165 offset:23552
	global_load_lds_dwordx4 v[224:225], off
	v_lshl_add_u64 v[226:227], s[36:37], 0, v[152:153]
	s_mov_b32 m0, s20
	s_nop 0
	global_load_lds_dwordx4 v[226:227], off
	s_barrier
	s_waitcnt lgkmcnt(0)
	s_setprio 1
	s_waitcnt lgkmcnt(0)
	v_mfma_f32_16x16x32_bf16 v[60:63], v[84:87], v[156:159], v[60:63]
	v_mfma_f32_16x16x32_bf16 v[64:67], v[140:143], v[156:159], v[64:67]
	v_mfma_f32_16x16x32_bf16 v[44:47], v[84:87], v[174:177], v[44:47]
	v_mfma_f32_16x16x32_bf16 v[48:51], v[140:143], v[174:177], v[48:51]
	v_mfma_f32_16x16x32_bf16 v[28:31], v[84:87], v[182:185], v[28:31]
	v_mfma_f32_16x16x32_bf16 v[32:35], v[140:143], v[182:185], v[32:35]
	v_mfma_f32_16x16x32_bf16 v[12:15], v[84:87], v[190:193], v[12:15]
	v_mfma_f32_16x16x32_bf16 v[8:11], v[140:143], v[190:193], v[8:11]
	v_mfma_f32_16x16x32_bf16 v[60:63], v[136:139], v[170:173], v[60:63]
	v_mfma_f32_16x16x32_bf16 v[64:67], v[144:147], v[170:173], v[64:67]
	v_mfma_f32_16x16x32_bf16 v[44:47], v[136:139], v[178:181], v[44:47]
	v_mfma_f32_16x16x32_bf16 v[48:51], v[144:147], v[178:181], v[48:51]
	v_mfma_f32_16x16x32_bf16 v[28:31], v[136:139], v[186:189], v[28:31]
	v_mfma_f32_16x16x32_bf16 v[32:35], v[144:147], v[186:189], v[32:35]
	v_mfma_f32_16x16x32_bf16 v[12:15], v[136:139], v[194:197], v[12:15]
	v_mfma_f32_16x16x32_bf16 v[8:11], v[144:147], v[194:197], v[8:11]
	s_setprio 0
	s_barrier
	s_add_u32 s58, s16, 0x40000
	s_addc_u32 s59, s17, 0
	s_mov_b32 m0, s64
	v_lshl_add_u64 v[84:85], s[58:59], 0, v[150:151]
	global_load_lds_dwordx4 v[84:85], off
	v_lshl_add_u64 v[84:85], s[58:59], 0, v[154:155]
	s_mov_b32 m0, s65
	s_nop 0
	global_load_lds_dwordx4 v[84:85], off
	s_waitcnt vmcnt(6)
	s_barrier
	s_setprio 1
	v_mfma_f32_16x16x32_bf16 v[52:55], v[198:201], v[156:159], v[52:55]
	v_mfma_f32_16x16x32_bf16 v[56:59], v[214:217], v[156:159], v[56:59]
	v_mfma_f32_16x16x32_bf16 v[36:39], v[198:201], v[174:177], v[36:39]
	v_mfma_f32_16x16x32_bf16 v[40:43], v[214:217], v[174:177], v[40:43]
	v_mfma_f32_16x16x32_bf16 v[20:23], v[198:201], v[182:185], v[20:23]
	v_mfma_f32_16x16x32_bf16 v[24:27], v[214:217], v[182:185], v[24:27]
	v_mfma_f32_16x16x32_bf16 v[4:7], v[198:201], v[190:193], v[4:7]
	v_mfma_f32_16x16x32_bf16 v[0:3], v[214:217], v[190:193], v[0:3]
	v_mfma_f32_16x16x32_bf16 v[52:55], v[210:213], v[170:173], v[52:55]
	v_mfma_f32_16x16x32_bf16 v[56:59], v[218:221], v[170:173], v[56:59]
	v_mfma_f32_16x16x32_bf16 v[36:39], v[210:213], v[178:181], v[36:39]
	v_mfma_f32_16x16x32_bf16 v[40:43], v[218:221], v[178:181], v[40:43]
	v_mfma_f32_16x16x32_bf16 v[20:23], v[210:213], v[186:189], v[20:23]
	v_mfma_f32_16x16x32_bf16 v[24:27], v[218:221], v[186:189], v[24:27]
	v_mfma_f32_16x16x32_bf16 v[4:7], v[210:213], v[194:197], v[4:7]
	v_mfma_f32_16x16x32_bf16 v[0:3], v[218:221], v[194:197], v[0:3]
	s_setprio 0
	s_barrier
	ds_read_b128 v[84:87], v167
	ds_read_b128 v[136:139], v167 offset:1024
	ds_read_b128 v[140:143], v167 offset:2048
	ds_read_b128 v[144:147], v167 offset:3072
	s_add_u32 s36, s36, 0x40000
	s_addc_u32 s37, s37, 0
	s_mov_b32 m0, s21
	v_lshl_add_u64 v[198:199], s[36:37], 0, v[148:149]
	ds_read_b128 v[156:159], v165 offset:32768
	ds_read_b128 v[170:173], v165 offset:33792
	ds_read_b128 v[174:177], v165 offset:34816
	ds_read_b128 v[178:181], v165 offset:35840
	ds_read_b128 v[182:185], v165 offset:36864
	ds_read_b128 v[186:189], v165 offset:37888
	ds_read_b128 v[190:193], v165 offset:38912
	ds_read_b128 v[194:197], v165 offset:39936
	global_load_lds_dwordx4 v[198:199], off
	v_lshl_add_u64 v[198:199], s[36:37], 0, v[152:153]
	s_mov_b32 m0, s22
	s_nop 0
	global_load_lds_dwordx4 v[198:199], off
	s_waitcnt lgkmcnt(8)
	s_barrier
	s_waitcnt lgkmcnt(0)
	s_setprio 1
	s_waitcnt lgkmcnt(0)
	v_mfma_f32_16x16x32_bf16 v[124:127], v[84:87], v[156:159], v[124:127]
	v_mfma_f32_16x16x32_bf16 v[120:123], v[140:143], v[156:159], v[120:123]
	v_mfma_f32_16x16x32_bf16 v[116:119], v[84:87], v[174:177], v[116:119]
	v_mfma_f32_16x16x32_bf16 v[112:115], v[140:143], v[174:177], v[112:115]
	v_mfma_f32_16x16x32_bf16 v[96:99], v[84:87], v[182:185], v[96:99]
	v_mfma_f32_16x16x32_bf16 v[100:103], v[140:143], v[182:185], v[100:103]
	v_mfma_f32_16x16x32_bf16 v[80:83], v[84:87], v[190:193], v[80:83]
	v_mfma_f32_16x16x32_bf16 v[76:79], v[140:143], v[190:193], v[76:79]
	v_mfma_f32_16x16x32_bf16 v[124:127], v[136:139], v[170:173], v[124:127]
	v_mfma_f32_16x16x32_bf16 v[120:123], v[144:147], v[170:173], v[120:123]
	v_mfma_f32_16x16x32_bf16 v[116:119], v[136:139], v[178:181], v[116:119]
	v_mfma_f32_16x16x32_bf16 v[112:115], v[144:147], v[178:181], v[112:115]
	v_mfma_f32_16x16x32_bf16 v[96:99], v[136:139], v[186:189], v[96:99]
	v_mfma_f32_16x16x32_bf16 v[100:103], v[144:147], v[186:189], v[100:103]
	v_mfma_f32_16x16x32_bf16 v[80:83], v[136:139], v[194:197], v[80:83]
	v_mfma_f32_16x16x32_bf16 v[76:79], v[144:147], v[194:197], v[76:79]
	s_setprio 0
	s_barrier
	s_mov_b32 m0, s66
	v_lshl_add_u64 v[160:161], v[160:161], 0, s[8:9]
	ds_read_b128 v[198:201], v168
	ds_read_b128 v[210:213], v168 offset:1024
	ds_read_b128 v[214:217], v168 offset:2048
	ds_read_b128 v[218:221], v168 offset:3072
	global_load_lds_dwordx4 v[160:161], off
	v_lshl_add_u64 v[160:161], v[222:223], 0, s[8:9]
	s_mov_b32 m0, s67
	s_nop 0
	global_load_lds_dwordx4 v[160:161], off
	s_barrier
	s_waitcnt lgkmcnt(0)
	s_setprio 1
	s_waitcnt lgkmcnt(0)
	v_mfma_f32_16x16x32_bf16 v[128:131], v[198:201], v[156:159], v[128:131]
	v_mfma_f32_16x16x32_bf16 v[132:135], v[214:217], v[156:159], v[132:135]
	v_mfma_f32_16x16x32_bf16 v[104:107], v[198:201], v[174:177], v[104:107]
	v_mfma_f32_16x16x32_bf16 v[108:111], v[214:217], v[174:177], v[108:111]
	v_mfma_f32_16x16x32_bf16 v[88:91], v[198:201], v[182:185], v[88:91]
	v_mfma_f32_16x16x32_bf16 v[92:95], v[214:217], v[182:185], v[92:95]
	v_mfma_f32_16x16x32_bf16 v[68:71], v[198:201], v[190:193], v[68:71]
	v_mfma_f32_16x16x32_bf16 v[72:75], v[214:217], v[190:193], v[72:75]
	v_mfma_f32_16x16x32_bf16 v[128:131], v[210:213], v[170:173], v[128:131]
	v_mfma_f32_16x16x32_bf16 v[132:135], v[218:221], v[170:173], v[132:135]
	v_mfma_f32_16x16x32_bf16 v[104:107], v[210:213], v[178:181], v[104:107]
	v_mfma_f32_16x16x32_bf16 v[108:111], v[218:221], v[178:181], v[108:111]
	v_mfma_f32_16x16x32_bf16 v[88:91], v[210:213], v[186:189], v[88:91]
	v_mfma_f32_16x16x32_bf16 v[92:95], v[218:221], v[186:189], v[92:95]
	v_mfma_f32_16x16x32_bf16 v[68:71], v[210:213], v[194:197], v[68:71]
	v_mfma_f32_16x16x32_bf16 v[72:75], v[218:221], v[194:197], v[72:75]
	s_setprio 0
	s_mov_b32 m0, s23
	v_lshl_add_u64 v[160:161], v[224:225], 0, s[8:9]
	s_barrier
	ds_read_b128 v[156:159], v165 offset:49152
	ds_read_b128 v[170:173], v165 offset:50176
	ds_read_b128 v[174:177], v165 offset:51200
	ds_read_b128 v[178:181], v165 offset:52224
	ds_read_b128 v[182:185], v165 offset:53248
	ds_read_b128 v[186:189], v165 offset:54272
	ds_read_b128 v[190:193], v165 offset:55296
	ds_read_b128 v[194:197], v165 offset:56320
	global_load_lds_dwordx4 v[160:161], off
	v_lshl_add_u64 v[160:161], v[226:227], 0, s[8:9]
	s_mov_b32 m0, s24
	s_nop 0
	global_load_lds_dwordx4 v[160:161], off
	s_barrier
	s_waitcnt lgkmcnt(0)
	s_setprio 1
	s_waitcnt lgkmcnt(0)
	v_mfma_f32_16x16x32_bf16 v[60:63], v[84:87], v[156:159], v[60:63]
	v_mfma_f32_16x16x32_bf16 v[64:67], v[140:143], v[156:159], v[64:67]
	v_mfma_f32_16x16x32_bf16 v[44:47], v[84:87], v[174:177], v[44:47]
	v_mfma_f32_16x16x32_bf16 v[48:51], v[140:143], v[174:177], v[48:51]
	v_mfma_f32_16x16x32_bf16 v[28:31], v[84:87], v[182:185], v[28:31]
	v_mfma_f32_16x16x32_bf16 v[32:35], v[140:143], v[182:185], v[32:35]
	v_mfma_f32_16x16x32_bf16 v[12:15], v[84:87], v[190:193], v[12:15]
	v_mfma_f32_16x16x32_bf16 v[8:11], v[140:143], v[190:193], v[8:11]
	v_mfma_f32_16x16x32_bf16 v[60:63], v[136:139], v[170:173], v[60:63]
	v_mfma_f32_16x16x32_bf16 v[64:67], v[144:147], v[170:173], v[64:67]
	v_mfma_f32_16x16x32_bf16 v[44:47], v[136:139], v[178:181], v[44:47]
	v_mfma_f32_16x16x32_bf16 v[48:51], v[144:147], v[178:181], v[48:51]
	v_mfma_f32_16x16x32_bf16 v[28:31], v[136:139], v[186:189], v[28:31]
	v_mfma_f32_16x16x32_bf16 v[32:35], v[144:147], v[186:189], v[32:35]
	v_mfma_f32_16x16x32_bf16 v[12:15], v[136:139], v[194:197], v[12:15]
	v_mfma_f32_16x16x32_bf16 v[8:11], v[144:147], v[194:197], v[8:11]
	s_setprio 0
	s_barrier
	s_add_u32 s16, s16, 0x40080
	s_addc_u32 s17, s17, 0
	s_mov_b32 m0, s68
	v_lshl_add_u64 v[84:85], s[16:17], 0, v[150:151]
	global_load_lds_dwordx4 v[84:85], off
	v_lshl_add_u64 v[84:85], s[16:17], 0, v[154:155]
	s_mov_b32 m0, s69
	s_nop 0
	global_load_lds_dwordx4 v[84:85], off
	s_waitcnt vmcnt(6)
	s_barrier
	s_setprio 1
	v_mfma_f32_16x16x32_bf16 v[52:55], v[198:201], v[156:159], v[52:55]
	v_mfma_f32_16x16x32_bf16 v[56:59], v[214:217], v[156:159], v[56:59]
	v_mfma_f32_16x16x32_bf16 v[36:39], v[198:201], v[174:177], v[36:39]
	v_mfma_f32_16x16x32_bf16 v[40:43], v[214:217], v[174:177], v[40:43]
	v_mfma_f32_16x16x32_bf16 v[20:23], v[198:201], v[182:185], v[20:23]
	v_mfma_f32_16x16x32_bf16 v[24:27], v[214:217], v[182:185], v[24:27]
	v_mfma_f32_16x16x32_bf16 v[4:7], v[198:201], v[190:193], v[4:7]
	v_mfma_f32_16x16x32_bf16 v[0:3], v[214:217], v[190:193], v[0:3]
	v_mfma_f32_16x16x32_bf16 v[52:55], v[210:213], v[170:173], v[52:55]
	v_mfma_f32_16x16x32_bf16 v[56:59], v[218:221], v[170:173], v[56:59]
	v_mfma_f32_16x16x32_bf16 v[36:39], v[210:213], v[178:181], v[36:39]
	v_mfma_f32_16x16x32_bf16 v[40:43], v[218:221], v[178:181], v[40:43]
	v_mfma_f32_16x16x32_bf16 v[20:23], v[210:213], v[186:189], v[20:23]
	v_mfma_f32_16x16x32_bf16 v[24:27], v[218:221], v[186:189], v[24:27]
	v_mfma_f32_16x16x32_bf16 v[4:7], v[210:213], v[194:197], v[4:7]
	v_mfma_f32_16x16x32_bf16 v[0:3], v[218:221], v[194:197], v[0:3]
	s_setprio 0
	s_add_i32 s56, s56, 2
	s_add_u32 s4, s4, 0x100
	s_addc_u32 s5, s5, 0
	s_cmp_lt_u32 s56, 6
	s_barrier
	s_cbranch_scc1 .LBB0_818
	s_mov_b64 s[98:99], exec
	v_readlane_b32 s100, v234, 18
	v_readlane_b32 s101, v234, 19
	v_mov_b32_e32 v242, 1
	s_mov_b64 exec, s[100:101]
	s_cbranch_execz .Lms_skip
	global_atomic_add v[244:245], v242, off offset:512
.Lms_skip:
	s_mov_b64 exec, s[98:99]
	s_sext_i32_i8 s2, s0
	s_mul_i32 s0, s14, 0x240000
	s_lshl_b32 s1, s2, 17
	s_add_i32 s0, s0, s1
	s_add_i32 s0, s0, 0xa8000
	v_add_u32_e32 v16, s0, v169
	v_mov_b32_e32 v17, 0
	v_lshl_add_u64 v[86:87], s[70:71], 0, v[16:17]
	v_add_co_u32_e32 v18, vcc, 0x10000, v86
	v_lshl_add_u32 v136, s14, 8, v162
	s_nop 0
	v_addc_co_u32_e32 v19, vcc, 0, v87, vcc
	global_load_dwordx4 v[140:143], v[18:19], off
	v_add_co_u32_e32 v18, vcc, 0x1000, v86
	v_lshl_or_b32 v85, s2, 8, v163
	s_nop 0
	v_addc_co_u32_e32 v19, vcc, 0, v87, vcc
	global_load_dwordx4 v[144:147], v[18:19], off
	global_load_dwordx4 v[148:151], v16, s[70:71]
	v_add_co_u32_e32 v16, vcc, 0x11000, v86
	v_ashrrev_i32_e32 v137, 31, v136
	s_nop 0
	v_addc_co_u32_e32 v17, vcc, 0, v87, vcc
	v_add_co_u32_e32 v156, vcc, 0x2000, v86
	global_load_dwordx4 v[152:155], v[16:17], off
	s_mov_b64 s[0:1], vcc
	v_add_co_u32_e32 v160, vcc, 0x12000, v86
	s_mov_b64 s[8:9], vcc
	v_add_co_u32_e32 v164, vcc, 0x3000, v86
	v_or_b32_e32 v138, s18, v85
	s_mov_b64 s[4:5], vcc
	v_add_co_u32_e32 v16, vcc, 0x13000, v86
	v_or_b32_e32 v84, 16, v136
	v_lshlrev_b64 v[158:159], 11, v[136:137]
	v_ashrrev_i32_e32 v139, 31, v138
	v_addc_co_u32_e32 v17, vcc, 0, v87, vcc
	v_ashrrev_i32_e32 v85, 31, v84
	v_lshl_add_u64 v[158:159], s[10:11], 0, v[158:159]
	v_lshlrev_b64 v[138:139], 1, v[138:139]
	v_addc_co_u32_e64 v157, vcc, 0, v87, s[0:1]
	global_load_dwordx4 v[16:19], v[16:17], off
	v_lshlrev_b64 v[168:169], 11, v[84:85]
	v_lshl_add_u64 v[84:85], v[158:159], 0, v[138:139]
	global_load_dwordx4 v[156:159], v[156:157], off
	v_addc_co_u32_e64 v161, vcc, 0, v87, s[8:9]
	v_addc_co_u32_e64 v165, vcc, 0, v87, s[4:5]
	global_load_dwordx4 v[160:163], v[160:161], off
	s_nop 0
	global_load_dwordx4 v[164:167], v[164:165], off
	s_mov_b32 s0, 0x120000
	v_readlane_b32 s80, v234, 43
	s_cmpk_gt_u32 s13, 0xff
	v_readlane_b32 s81, v234, 44
	s_waitcnt vmcnt(0)
	v_lshlrev_b32_e32 v172, 16, v140
	v_and_b32_e32 v173, 0xffff0000, v140
	v_lshlrev_b32_e32 v140, 16, v141
	v_and_b32_e32 v141, 0xffff0000, v141
	v_lshlrev_b32_e32 v170, 16, v142
	v_and_b32_e32 v171, 0xffff0000, v142
	v_lshlrev_b32_e32 v142, 16, v143
	v_and_b32_e32 v143, 0xffff0000, v143
	v_pk_mul_f32 v[130:131], v[130:131], v[140:141]
	v_pk_mul_f32 v[128:129], v[128:129], v[172:173]
	v_pk_mul_f32 v[134:135], v[134:135], v[142:143]
	v_pk_mul_f32 v[132:133], v[132:133], v[170:171]
	v_cvt_pk_bf16_f32 v128, v128, v129
	v_cvt_pk_bf16_f32 v129, v130, v131
	v_cvt_pk_bf16_f32 v131, v134, v135
	v_lshlrev_b32_e32 v134, 16, v149
	v_cvt_pk_bf16_f32 v130, v132, v133
	global_store_dwordx4 v[84:85], v[128:131], off offset:256 sc1
	v_lshlrev_b32_e32 v132, 16, v148
	v_and_b32_e32 v133, 0xffff0000, v148
	v_lshlrev_b32_e32 v128, 16, v150
	v_and_b32_e32 v129, 0xffff0000, v150
	v_lshlrev_b32_e32 v130, 16, v151
	v_and_b32_e32 v131, 0xffff0000, v151
	v_and_b32_e32 v135, 0xffff0000, v149
	v_pk_mul_f32 v[130:131], v[122:123], v[130:131]
	v_pk_mul_f32 v[122:123], v[120:121], v[128:129]
	v_pk_mul_f32 v[120:121], v[124:125], v[132:133]
	v_pk_mul_f32 v[126:127], v[126:127], v[134:135]
	v_cvt_pk_bf16_f32 v120, v120, v121
	v_lshlrev_b32_e32 v140, 16, v146
	v_cvt_pk_bf16_f32 v121, v126, v127
	v_cvt_pk_bf16_f32 v122, v122, v123
	v_cvt_pk_bf16_f32 v123, v130, v131
	global_store_dwordx4 v[84:85], v[120:123], off sc1
	v_and_b32_e32 v141, 0xffff0000, v146
	s_nop 0
	v_lshlrev_b32_e32 v120, 16, v147
	v_and_b32_e32 v121, 0xffff0000, v147
	v_pk_mul_f32 v[120:121], v[114:115], v[120:121]
	v_pk_mul_f32 v[114:115], v[112:113], v[140:141]
	v_lshlrev_b32_e32 v112, 16, v144
	v_and_b32_e32 v113, 0xffff0000, v144
	v_lshlrev_b32_e32 v122, 16, v145
	v_and_b32_e32 v123, 0xffff0000, v145
	v_pk_mul_f32 v[112:113], v[116:117], v[112:113]
	v_lshl_add_u64 v[116:117], s[10:11], 0, v[168:169]
	v_pk_mul_f32 v[118:119], v[118:119], v[122:123]
	v_cvt_pk_bf16_f32 v112, v112, v113
	v_cvt_pk_bf16_f32 v114, v114, v115
	v_cvt_pk_bf16_f32 v115, v120, v121
	v_lshl_add_u64 v[116:117], v[116:117], 0, v[138:139]
	v_cvt_pk_bf16_f32 v113, v118, v119
	global_store_dwordx4 v[116:117], v[112:115], off sc1
	s_nop 1
	v_lshlrev_b32_e32 v112, 16, v154
	v_and_b32_e32 v113, 0xffff0000, v154
	v_lshlrev_b32_e32 v114, 16, v155
	v_and_b32_e32 v115, 0xffff0000, v155
	v_pk_mul_f32 v[110:111], v[110:111], v[114:115]
	v_pk_mul_f32 v[108:109], v[108:109], v[112:113]
	v_lshlrev_b32_e32 v112, 16, v152
	v_and_b32_e32 v113, 0xffff0000, v152
	v_lshlrev_b32_e32 v114, 16, v153
	v_and_b32_e32 v115, 0xffff0000, v153
	v_pk_mul_f32 v[106:107], v[106:107], v[114:115]
	v_pk_mul_f32 v[104:105], v[104:105], v[112:113]
	s_nop 0
	v_cvt_pk_bf16_f32 v104, v104, v105
	v_cvt_pk_bf16_f32 v105, v106, v107
	v_cvt_pk_bf16_f32 v106, v108, v109
	v_cvt_pk_bf16_f32 v107, v110, v111
	global_store_dwordx4 v[116:117], v[104:107], off offset:256 sc1
	v_lshlrev_b32_e32 v108, 16, v159
	v_and_b32_e32 v109, 0xffff0000, v159
	v_or_b32_e32 v104, 32, v136
	v_lshlrev_b32_e32 v106, 16, v158
	v_and_b32_e32 v107, 0xffff0000, v158
	v_ashrrev_i32_e32 v105, 31, v104
	v_pk_mul_f32 v[102:103], v[102:103], v[108:109]
	v_pk_mul_f32 v[100:101], v[100:101], v[106:107]
	v_lshlrev_b32_e32 v106, 16, v156
	v_and_b32_e32 v107, 0xffff0000, v156
	v_lshlrev_b32_e32 v108, 16, v157
	v_and_b32_e32 v109, 0xffff0000, v157
	v_lshlrev_b64 v[104:105], 11, v[104:105]
	v_pk_mul_f32 v[98:99], v[98:99], v[108:109]
	v_pk_mul_f32 v[96:97], v[96:97], v[106:107]
	s_nop 0
	v_cvt_pk_bf16_f32 v96, v96, v97
	v_cvt_pk_bf16_f32 v97, v98, v99
	v_cvt_pk_bf16_f32 v98, v100, v101
	v_lshl_add_u64 v[100:101], s[10:11], 0, v[104:105]
	v_lshl_add_u64 v[100:101], v[100:101], 0, v[138:139]
	v_cvt_pk_bf16_f32 v99, v102, v103
	global_store_dwordx4 v[100:101], v[96:99], off sc1
	s_nop 1
	v_lshlrev_b32_e32 v96, 16, v162
	v_and_b32_e32 v97, 0xffff0000, v162
	v_lshlrev_b32_e32 v98, 16, v163
	v_and_b32_e32 v99, 0xffff0000, v163
	v_pk_mul_f32 v[92:93], v[92:93], v[96:97]
	v_lshlrev_b32_e32 v96, 16, v160
	v_and_b32_e32 v97, 0xffff0000, v160
	v_pk_mul_f32 v[94:95], v[94:95], v[98:99]
	v_lshlrev_b32_e32 v98, 16, v161
	v_and_b32_e32 v99, 0xffff0000, v161
	v_pk_mul_f32 v[88:89], v[88:89], v[96:97]
	v_pk_mul_f32 v[90:91], v[90:91], v[98:99]
	v_cvt_pk_bf16_f32 v88, v88, v89
	s_nop 0
	v_cvt_pk_bf16_f32 v89, v90, v91
	v_cvt_pk_bf16_f32 v90, v92, v93
	v_cvt_pk_bf16_f32 v91, v94, v95
	global_store_dwordx4 v[100:101], v[88:91], off offset:256 sc1
	v_lshlrev_b32_e32 v92, 16, v167
	v_and_b32_e32 v93, 0xffff0000, v167
	v_or_b32_e32 v88, 48, v136
	v_ashrrev_i32_e32 v89, 31, v88
	v_lshlrev_b32_e32 v90, 16, v166
	v_and_b32_e32 v91, 0xffff0000, v166
	v_lshlrev_b64 v[88:89], 11, v[88:89]
	v_pk_mul_f32 v[92:93], v[78:79], v[92:93]
	v_pk_mul_f32 v[78:79], v[76:77], v[90:91]
	v_lshlrev_b32_e32 v76, 16, v164
	v_and_b32_e32 v77, 0xffff0000, v164
	v_lshlrev_b32_e32 v90, 16, v165
	v_and_b32_e32 v91, 0xffff0000, v165
	v_pk_mul_f32 v[76:77], v[80:81], v[76:77]
	v_lshl_add_u64 v[80:81], s[10:11], 0, v[88:89]
	v_pk_mul_f32 v[82:83], v[82:83], v[90:91]
	v_cvt_pk_bf16_f32 v76, v76, v77
	v_lshl_add_u64 v[80:81], v[80:81], 0, v[138:139]
	v_cvt_pk_bf16_f32 v77, v82, v83
	v_cvt_pk_bf16_f32 v78, v78, v79
	v_cvt_pk_bf16_f32 v79, v92, v93
	global_store_dwordx4 v[80:81], v[76:79], off sc1
	s_nop 1
	v_lshlrev_b32_e32 v76, 16, v18
	v_and_b32_e32 v77, 0xffff0000, v18
	v_lshlrev_b32_e32 v18, 16, v19
	v_and_b32_e32 v19, 0xffff0000, v19
	v_pk_mul_f32 v[74:75], v[74:75], v[18:19]
	v_pk_mul_f32 v[18:19], v[72:73], v[76:77]
	v_lshlrev_b32_e32 v72, 16, v16
	v_and_b32_e32 v73, 0xffff0000, v16
	v_lshlrev_b32_e32 v16, 16, v17
	v_and_b32_e32 v17, 0xffff0000, v17
	v_pk_mul_f32 v[70:71], v[70:71], v[16:17]
	v_pk_mul_f32 v[16:17], v[68:69], v[72:73]
	v_cvt_pk_bf16_f32 v18, v18, v19
	v_cvt_pk_bf16_f32 v19, v74, v75
	s_nop 0
	v_cvt_pk_bf16_f32 v16, v16, v17
	v_cvt_pk_bf16_f32 v17, v70, v71
	global_store_dwordx4 v[80:81], v[16:19], off offset:256 sc1
	s_nop 1
	v_add_co_u32_e32 v16, vcc, s0, v86
	s_mov_b32 s0, 0x131000
	s_nop 0
	v_addc_co_u32_e32 v17, vcc, 0, v87, vcc
	global_load_dwordx4 v[72:75], v[16:17], off
	v_add_co_u32_e32 v16, vcc, s0, v86
	s_mov_b32 s0, 0x122000
	s_nop 0
	v_addc_co_u32_e32 v17, vcc, 0, v87, vcc
	global_load_dwordx4 v[76:79], v[16:17], off offset:-4096
	v_add_co_u32_e32 v18, vcc, s0, v86
	s_mov_b32 s0, 0x123000
	s_nop 0
	v_addc_co_u32_e32 v19, vcc, 0, v87, vcc
	global_load_dwordx4 v[80:83], v[18:19], off offset:-4096
	global_load_dwordx4 v[88:91], v[16:17], off
	v_add_co_u32_e32 v16, vcc, s0, v86
	s_mov_b32 s0, 0x133000
	s_nop 0
	v_addc_co_u32_e32 v17, vcc, 0, v87, vcc
	global_load_dwordx4 v[68:71], v[16:17], off
	global_load_dwordx4 v[92:95], v[18:19], off
	v_add_co_u32_e32 v16, vcc, s0, v86
	s_mov_b64 s[0:1], 0x40000
	s_nop 0
	v_addc_co_u32_e32 v17, vcc, 0, v87, vcc
	global_load_dwordx4 v[96:99], v[16:17], off offset:-4096
	s_nop 0
	global_load_dwordx4 v[16:19], v[16:17], off
	s_waitcnt vmcnt(0)
	v_lshlrev_b32_e32 v86, 16, v74
	v_and_b32_e32 v87, 0xffff0000, v74
	v_lshlrev_b32_e32 v74, 16, v75
	v_and_b32_e32 v75, 0xffff0000, v75
	v_pk_mul_f32 v[66:67], v[66:67], v[74:75]
	v_lshlrev_b32_e32 v74, 16, v72
	v_and_b32_e32 v75, 0xffff0000, v72
	v_lshlrev_b32_e32 v72, 16, v73
	v_and_b32_e32 v73, 0xffff0000, v73
	v_pk_mul_f32 v[64:65], v[64:65], v[86:87]
	v_pk_mul_f32 v[62:63], v[62:63], v[72:73]
	v_pk_mul_f32 v[60:61], v[60:61], v[74:75]
	s_nop 0
	v_cvt_pk_bf16_f32 v60, v60, v61
	v_cvt_pk_bf16_f32 v61, v62, v63
	v_cvt_pk_bf16_f32 v62, v64, v65
	v_lshl_add_u64 v[64:65], v[84:85], 0, s[0:1]
	s_mov_b32 s0, 0x40000
	v_cvt_pk_bf16_f32 v63, v66, v67
	v_add_co_u32_e32 v66, vcc, s0, v84
	s_mov_b64 s[0:1], 0x48000
	s_nop 0
	v_addc_co_u32_e32 v67, vcc, 0, v85, vcc
	global_store_dwordx4 v[66:67], v[60:63], off sc1
	s_nop 1
	v_lshlrev_b32_e32 v60, 16, v78
	v_and_b32_e32 v61, 0xffff0000, v78
	v_lshlrev_b32_e32 v62, 16, v79
	v_and_b32_e32 v63, 0xffff0000, v79
	v_pk_mul_f32 v[58:59], v[58:59], v[62:63]
	v_pk_mul_f32 v[56:57], v[56:57], v[60:61]
	v_lshlrev_b32_e32 v60, 16, v76
	v_and_b32_e32 v61, 0xffff0000, v76
	v_lshlrev_b32_e32 v62, 16, v77
	v_and_b32_e32 v63, 0xffff0000, v77
	v_pk_mul_f32 v[54:55], v[54:55], v[62:63]
	v_pk_mul_f32 v[52:53], v[52:53], v[60:61]
	s_nop 0
	v_cvt_pk_bf16_f32 v52, v52, v53
	v_cvt_pk_bf16_f32 v53, v54, v55
	v_cvt_pk_bf16_f32 v54, v56, v57
	v_cvt_pk_bf16_f32 v55, v58, v59
	global_store_dwordx4 v[64:65], v[52:55], off offset:256 sc1
	s_nop 1
	v_lshlrev_b32_e32 v52, 16, v82
	v_and_b32_e32 v53, 0xffff0000, v82
	v_lshlrev_b32_e32 v54, 16, v83
	v_and_b32_e32 v55, 0xffff0000, v83
	v_pk_mul_f32 v[50:51], v[50:51], v[54:55]
	v_pk_mul_f32 v[48:49], v[48:49], v[52:53]
	v_lshlrev_b32_e32 v52, 16, v80
	v_and_b32_e32 v53, 0xffff0000, v80
	v_lshlrev_b32_e32 v54, 16, v81
	v_and_b32_e32 v55, 0xffff0000, v81
	v_pk_mul_f32 v[46:47], v[46:47], v[54:55]
	v_pk_mul_f32 v[44:45], v[44:45], v[52:53]
	s_nop 0
	v_cvt_pk_bf16_f32 v44, v44, v45
	v_cvt_pk_bf16_f32 v45, v46, v47
	v_cvt_pk_bf16_f32 v46, v48, v49
	v_lshl_add_u64 v[48:49], v[84:85], 0, s[0:1]
	s_mov_b32 s0, 0x48000
	v_cvt_pk_bf16_f32 v47, v50, v51
	v_add_co_u32_e32 v50, vcc, s0, v84
	s_mov_b64 s[0:1], 0x50000
	s_nop 0
	v_addc_co_u32_e32 v51, vcc, 0, v85, vcc
	global_store_dwordx4 v[50:51], v[44:47], off sc1
	s_nop 1
	v_lshlrev_b32_e32 v44, 16, v90
	v_and_b32_e32 v45, 0xffff0000, v90
	v_lshlrev_b32_e32 v46, 16, v91
	v_and_b32_e32 v47, 0xffff0000, v91
	v_pk_mul_f32 v[42:43], v[42:43], v[46:47]
	v_pk_mul_f32 v[40:41], v[40:41], v[44:45]
	v_lshlrev_b32_e32 v44, 16, v88
	v_and_b32_e32 v45, 0xffff0000, v88
	v_lshlrev_b32_e32 v46, 16, v89
	v_and_b32_e32 v47, 0xffff0000, v89
	v_pk_mul_f32 v[38:39], v[38:39], v[46:47]
	v_pk_mul_f32 v[36:37], v[36:37], v[44:45]
	s_nop 0
	v_cvt_pk_bf16_f32 v36, v36, v37
	v_cvt_pk_bf16_f32 v37, v38, v39
	v_cvt_pk_bf16_f32 v38, v40, v41
	v_cvt_pk_bf16_f32 v39, v42, v43
	global_store_dwordx4 v[48:49], v[36:39], off offset:256 sc1
	s_nop 1
	v_lshlrev_b32_e32 v36, 16, v94
	v_and_b32_e32 v37, 0xffff0000, v94
	v_lshlrev_b32_e32 v38, 16, v95
	v_and_b32_e32 v39, 0xffff0000, v95
	v_pk_mul_f32 v[34:35], v[34:35], v[38:39]
	v_pk_mul_f32 v[32:33], v[32:33], v[36:37]
	v_lshlrev_b32_e32 v36, 16, v92
	v_and_b32_e32 v37, 0xffff0000, v92
	v_lshlrev_b32_e32 v38, 16, v93
	v_and_b32_e32 v39, 0xffff0000, v93
	v_pk_mul_f32 v[30:31], v[30:31], v[38:39]
	v_pk_mul_f32 v[28:29], v[28:29], v[36:37]
	s_nop 0
	v_cvt_pk_bf16_f32 v28, v28, v29
	v_cvt_pk_bf16_f32 v29, v30, v31
	v_cvt_pk_bf16_f32 v30, v32, v33
	v_lshl_add_u64 v[32:33], v[84:85], 0, s[0:1]
	s_mov_b32 s0, 0x50000
	v_cvt_pk_bf16_f32 v31, v34, v35
	v_add_co_u32_e32 v34, vcc, s0, v84
	s_mov_b64 s[0:1], 0x58000
	s_nop 0
	v_addc_co_u32_e32 v35, vcc, 0, v85, vcc
	global_store_dwordx4 v[34:35], v[28:31], off sc1
	s_nop 1
	v_lshlrev_b32_e32 v28, 16, v98
	v_and_b32_e32 v29, 0xffff0000, v98
	v_lshlrev_b32_e32 v30, 16, v99
	v_and_b32_e32 v31, 0xffff0000, v99
	v_pk_mul_f32 v[26:27], v[26:27], v[30:31]
	v_pk_mul_f32 v[24:25], v[24:25], v[28:29]
	v_lshlrev_b32_e32 v28, 16, v96
	v_and_b32_e32 v29, 0xffff0000, v96
	v_lshlrev_b32_e32 v30, 16, v97
	v_and_b32_e32 v31, 0xffff0000, v97
	v_pk_mul_f32 v[22:23], v[22:23], v[30:31]
	v_pk_mul_f32 v[20:21], v[20:21], v[28:29]
	s_nop 0
	v_cvt_pk_bf16_f32 v20, v20, v21
	v_cvt_pk_bf16_f32 v21, v22, v23
	v_cvt_pk_bf16_f32 v22, v24, v25
	v_cvt_pk_bf16_f32 v23, v26, v27
	global_store_dwordx4 v[32:33], v[20:23], off offset:256 sc1
	s_nop 1
	v_lshlrev_b32_e32 v20, 16, v70
	v_and_b32_e32 v21, 0xffff0000, v70
	v_lshlrev_b32_e32 v22, 16, v71
	v_and_b32_e32 v23, 0xffff0000, v71
	v_pk_mul_f32 v[22:23], v[10:11], v[22:23]
	v_pk_mul_f32 v[10:11], v[8:9], v[20:21]
	v_lshlrev_b32_e32 v8, 16, v68
	v_and_b32_e32 v9, 0xffff0000, v68
	v_lshlrev_b32_e32 v20, 16, v69
	v_and_b32_e32 v21, 0xffff0000, v69
	v_pk_mul_f32 v[14:15], v[14:15], v[20:21]
	v_pk_mul_f32 v[8:9], v[12:13], v[8:9]
	v_lshl_add_u64 v[12:13], v[84:85], 0, s[0:1]
	s_mov_b32 s0, 0x58000
	v_cvt_pk_bf16_f32 v8, v8, v9
	v_cvt_pk_bf16_f32 v9, v14, v15
	v_add_co_u32_e32 v14, vcc, s0, v84
	v_cvt_pk_bf16_f32 v10, v10, v11
	v_cvt_pk_bf16_f32 v11, v22, v23
	s_nop 1
	v_addc_co_u32_e32 v15, vcc, 0, v85, vcc
	global_store_dwordx4 v[14:15], v[8:11], off sc1
	s_nop 1
	v_lshlrev_b32_e32 v8, 16, v18
	v_and_b32_e32 v9, 0xffff0000, v18
	v_lshlrev_b32_e32 v10, 16, v19
	v_and_b32_e32 v11, 0xffff0000, v19
	v_pk_mul_f32 v[10:11], v[2:3], v[10:11]
	v_pk_mul_f32 v[2:3], v[0:1], v[8:9]
	v_lshlrev_b32_e32 v0, 16, v16
	v_and_b32_e32 v1, 0xffff0000, v16
	v_lshlrev_b32_e32 v8, 16, v17
	v_and_b32_e32 v9, 0xffff0000, v17
	v_pk_mul_f32 v[0:1], v[4:5], v[0:1]
	v_pk_mul_f32 v[6:7], v[6:7], v[8:9]
	v_cvt_pk_bf16_f32 v0, v0, v1
	v_cvt_pk_bf16_f32 v2, v2, v3
	v_cvt_pk_bf16_f32 v3, v10, v11
	s_nop 0
	v_cvt_pk_bf16_f32 v1, v6, v7
	global_store_dwordx4 v[12:13], v[0:3], off offset:256 sc1
	s_waitcnt vmcnt(0)
	s_cbranch_scc1 .LBB0_821
	s_barrier

.LBB0_822:
	s_getreg_b32 s2, hwreg(HW_REG_XCC_ID, 0, 4)
	s_waitcnt vmcnt(0)
	s_waitcnt lgkmcnt(0)
	s_barrier
	s_mov_b64 s[0:1], exec
	v_readlane_b32 s4, v234, 18
	v_readlane_b32 s5, v234, 19
	v_readlane_b32 s60, v234, 0
	s_and_b64 s[4:5], s[0:1], s[4:5]
	v_readlane_b32 s62, v234, 2
	v_readlane_b32 s63, v234, 3
	v_readlane_b32 s61, v234, 1
	v_readlane_b32 s64, v234, 4
	v_readlane_b32 s65, v234, 5
	v_readlane_b32 s66, v234, 6
	v_readlane_b32 s67, v234, 7
	v_readlane_b32 s68, v234, 8
	v_readlane_b32 s69, v234, 9
	v_readlane_b32 s70, v234, 10
	v_readlane_b32 s71, v234, 11
	v_readlane_b32 s72, v234, 12
	v_readlane_b32 s73, v234, 13
	v_readlane_b32 s74, v234, 14
	v_readlane_b32 s75, v234, 15
	s_mov_b64 exec, s[4:5]
	s_cbranch_execz .LBB0_874
	v_readlane_b32 s98, v243, 0
	s_mov_b32 s99, 0
	v_mov_b32_e32 v242, 1
	s_mov_b32 s100, 0
	v_lshl_add_u64 v[246:247], v[244:245], 0, s[98:99]
	global_atomic_add v[246:247], v242, off
.Lg5_spin:
	global_load_dword v241, v[246:247], off sc1
	global_load_dword v240, v[244:245], off offset:512 sc1
	s_waitcnt vmcnt(0)
	v_subrev_u32_e32 v241, 4, v241
	v_subrev_u32_e32 v240, 0x100, v240
	v_or_b32_e32 v241, v241, v240
	v_cmp_gt_i32_e32 vcc, 0, v241
	s_cbranch_vccz .Lg5_acq
	s_sleep 1
	s_add_u32 s100, s100, 1
	s_cmp_lt_u32 s100, 0x1000
	s_cbranch_scc1 .Lg5_spin
.Lg5_acq:
	buffer_inv sc1
	s_waitcnt vmcnt(0)

.LBB0_879:
	s_or_b64 exec, exec, s[4:5]
	s_waitcnt vmcnt(13)
	v_mfma_f32_16x16x32_bf16 v[8:11], v[16:19], v[8:11], 0
	s_barrier
	s_waitcnt vmcnt(12)
	v_mfma_f32_16x16x32_bf16 v[8:11], v[20:23], v[12:15], v[8:11]
	s_waitcnt vmcnt(9)
	v_mfma_f32_16x16x32_bf16 v[8:11], v[32:35], v[24:27], v[8:11]
	s_waitcnt vmcnt(8)
	v_mfma_f32_16x16x32_bf16 v[8:11], v[36:39], v[28:31], v[8:11]
	s_waitcnt vmcnt(5)
	v_mfma_f32_16x16x32_bf16 v[8:11], v[56:59], v[40:43], v[8:11]
	s_waitcnt vmcnt(4)
	v_mfma_f32_16x16x32_bf16 v[8:11], v[60:63], v[48:51], v[8:11]
	s_waitcnt vmcnt(1)
	v_mfma_f32_16x16x32_bf16 v[8:11], v[68:71], v[64:67], v[8:11]
	s_waitcnt vmcnt(0)
	v_mfma_f32_16x16x32_bf16 v[8:11], v[52:55], v[44:47], v[8:11]
	s_nop 7
	ds_write_b128 v82, v[8:11]
	s_waitcnt lgkmcnt(0)
	s_barrier
	s_and_saveexec_b64 s[4:5], s[0:1]
	s_cbranch_execz .LBB0_876
	ds_read_b128 v[8:11], v82
	ds_read_b128 v[12:15], v83 offset:2048
	ds_read_b128 v[16:19], v83 offset:4096
	ds_read_b128 v[20:23], v83 offset:6144
	s_waitcnt lgkmcnt(2)
	v_pk_add_f32 v[10:11], v[10:11], v[14:15]
	v_pk_add_f32 v[8:9], v[8:9], v[12:13]
	s_waitcnt lgkmcnt(0)
	v_pk_add_f32 v[14:15], v[16:17], v[20:21]
	v_pk_add_f32 v[12:13], v[18:19], v[22:23]
	v_pk_add_f32 v[8:9], v[8:9], v[14:15]
	v_pk_add_f32 v[10:11], v[10:11], v[12:13]
	v_pk_fma_f32 v[0:1], v[4:5], v[8:9], v[0:1]
	v_lshl_add_u64 v[4:5], s[2:3], 0, v[72:73]
	v_pk_fma_f32 v[2:3], v[6:7], v[10:11], v[2:3]
	v_lshl_add_u64 v[4:5], v[78:79], 2, v[4:5]
	global_store_dwordx4 v[4:5], v[0:3], off sc1
	s_branch .LBB0_876

.LBB0_898:
	v_add_u32_e32 v158, s64, v144
	s_add_u32 s26, s6, s56
	ds_read_b128 v[146:149], v158
	ds_read_b128 v[150:153], v158 offset:1024
	ds_read_b128 v[154:157], v158 offset:2048
	ds_read_b128 v[158:161], v158 offset:3072
	s_addc_u32 s27, s7, s57
	s_add_u32 s26, s26, 0x100
	s_addc_u32 s27, s27, 0
	s_add_u32 s58, s67, s56
	s_addc_u32 s59, s68, s57
	s_cmpk_eq_i32 s56, 0x700
	s_cselect_b32 s61, s17, s27
	s_cselect_b32 s60, s69, s26
	s_cselect_b32 s59, s15, s59
	s_cselect_b32 s58, s70, s58
	v_lshl_add_u64 v[194:195], v[140:141], 0, s[56:57]
	s_add_i32 m0, s3, 0xc000
	ds_read_b128 v[162:165], v145
	ds_read_b128 v[166:169], v145 offset:1024
	ds_read_b128 v[170:173], v145 offset:2048
	ds_read_b128 v[174:177], v145 offset:3072
	ds_read_b128 v[178:181], v145 offset:4096
	ds_read_b128 v[182:185], v145 offset:5120
	ds_read_b128 v[186:189], v145 offset:6144
	ds_read_b128 v[190:193], v145 offset:7168
	global_load_lds_dwordx4 v[194:195], off
	v_lshl_add_u64 v[194:195], v[142:143], 0, s[56:57]
	s_add_i32 m0, s3, 0xe000
	s_nop 0
	global_load_lds_dwordx4 v[194:195], off
	s_waitcnt lgkmcnt(8)
	s_barrier
	s_waitcnt lgkmcnt(0)
	s_setprio 1
	s_waitcnt lgkmcnt(0)
	v_mfma_f32_16x16x32_bf16 v[124:127], v[146:149], v[162:165], v[124:127]
	v_mfma_f32_16x16x32_bf16 v[120:123], v[154:157], v[162:165], v[120:123]
	v_mfma_f32_16x16x32_bf16 v[108:111], v[146:149], v[170:173], v[108:111]
	v_mfma_f32_16x16x32_bf16 v[104:107], v[154:157], v[170:173], v[104:107]
	v_mfma_f32_16x16x32_bf16 v[92:95], v[146:149], v[178:181], v[92:95]
	v_mfma_f32_16x16x32_bf16 v[88:91], v[154:157], v[178:181], v[88:91]
	v_mfma_f32_16x16x32_bf16 v[76:79], v[146:149], v[186:189], v[76:79]
	v_mfma_f32_16x16x32_bf16 v[72:75], v[154:157], v[186:189], v[72:75]
	v_mfma_f32_16x16x32_bf16 v[124:127], v[150:153], v[166:169], v[124:127]
	v_mfma_f32_16x16x32_bf16 v[120:123], v[158:161], v[166:169], v[120:123]
	v_mfma_f32_16x16x32_bf16 v[108:111], v[150:153], v[174:177], v[108:111]
	v_mfma_f32_16x16x32_bf16 v[104:107], v[158:161], v[174:177], v[104:107]
	v_mfma_f32_16x16x32_bf16 v[92:95], v[150:153], v[182:185], v[92:95]
	v_mfma_f32_16x16x32_bf16 v[88:91], v[158:161], v[182:185], v[88:91]
	v_mfma_f32_16x16x32_bf16 v[76:79], v[150:153], v[190:193], v[76:79]
	v_mfma_f32_16x16x32_bf16 v[72:75], v[158:161], v[190:193], v[72:75]
	s_setprio 0
	s_barrier
	s_add_i32 s26, s64, s22
	v_add_u32_e32 v209, s65, v144
	v_lshl_add_u64 v[218:219], s[58:59], 0, v[128:129]
	s_mov_b32 m0, s26
	ds_read_b128 v[194:197], v209
	ds_read_b128 v[198:201], v209 offset:1024
	ds_read_b128 v[210:213], v209 offset:2048
	ds_read_b128 v[214:217], v209 offset:3072
	global_load_lds_dwordx4 v[218:219], off
	v_lshl_add_u64 v[220:221], s[58:59], 0, v[130:131]
	s_add_i32 m0, s26, 0x2000
	s_nop 0
	global_load_lds_dwordx4 v[220:221], off
	s_barrier
	s_waitcnt lgkmcnt(0)
	s_setprio 1
	s_waitcnt lgkmcnt(0)
	v_mfma_f32_16x16x32_bf16 v[116:119], v[194:197], v[162:165], v[116:119]
	v_mfma_f32_16x16x32_bf16 v[112:115], v[210:213], v[162:165], v[112:115]
	v_mfma_f32_16x16x32_bf16 v[100:103], v[194:197], v[170:173], v[100:103]
	v_mfma_f32_16x16x32_bf16 v[96:99], v[210:213], v[170:173], v[96:99]
	v_mfma_f32_16x16x32_bf16 v[84:87], v[194:197], v[178:181], v[84:87]
	v_mfma_f32_16x16x32_bf16 v[80:83], v[210:213], v[178:181], v[80:83]
	v_mfma_f32_16x16x32_bf16 v[68:71], v[194:197], v[186:189], v[68:71]
	v_mfma_f32_16x16x32_bf16 v[64:67], v[210:213], v[186:189], v[64:67]
	v_mfma_f32_16x16x32_bf16 v[116:119], v[198:201], v[166:169], v[116:119]
	v_mfma_f32_16x16x32_bf16 v[112:115], v[214:217], v[166:169], v[112:115]
	v_mfma_f32_16x16x32_bf16 v[100:103], v[198:201], v[174:177], v[100:103]
	v_mfma_f32_16x16x32_bf16 v[96:99], v[214:217], v[174:177], v[96:99]
	v_mfma_f32_16x16x32_bf16 v[84:87], v[198:201], v[182:185], v[84:87]
	v_mfma_f32_16x16x32_bf16 v[80:83], v[214:217], v[182:185], v[80:83]
	v_mfma_f32_16x16x32_bf16 v[68:71], v[198:201], v[190:193], v[68:71]
	v_mfma_f32_16x16x32_bf16 v[64:67], v[214:217], v[190:193], v[64:67]
	s_setprio 0
	s_mov_b32 m0, s3
	v_lshl_add_u64 v[222:223], s[60:61], 0, v[128:129]
	s_barrier
	ds_read_b128 v[162:165], v145 offset:16384
	ds_read_b128 v[166:169], v145 offset:17408
	ds_read_b128 v[170:173], v145 offset:18432
	ds_read_b128 v[174:177], v145 offset:19456
	ds_read_b128 v[178:181], v145 offset:20480
	ds_read_b128 v[182:185], v145 offset:21504
	ds_read_b128 v[186:189], v145 offset:22528
	ds_read_b128 v[190:193], v145 offset:23552
	global_load_lds_dwordx4 v[222:223], off
	v_lshl_add_u64 v[224:225], s[60:61], 0, v[130:131]
	s_mov_b32 m0, s23
	s_nop 0
	global_load_lds_dwordx4 v[224:225], off
	s_barrier
	s_waitcnt lgkmcnt(0)
	s_setprio 1
	s_waitcnt lgkmcnt(0)
	v_mfma_f32_16x16x32_bf16 v[60:63], v[146:149], v[162:165], v[60:63]
	v_mfma_f32_16x16x32_bf16 v[56:59], v[154:157], v[162:165], v[56:59]
	v_mfma_f32_16x16x32_bf16 v[44:47], v[146:149], v[170:173], v[44:47]
	v_mfma_f32_16x16x32_bf16 v[40:43], v[154:157], v[170:173], v[40:43]
	v_mfma_f32_16x16x32_bf16 v[28:31], v[146:149], v[178:181], v[28:31]
	v_mfma_f32_16x16x32_bf16 v[24:27], v[154:157], v[178:181], v[24:27]
	v_mfma_f32_16x16x32_bf16 v[12:15], v[146:149], v[186:189], v[12:15]
	v_mfma_f32_16x16x32_bf16 v[8:11], v[154:157], v[186:189], v[8:11]
	v_mfma_f32_16x16x32_bf16 v[60:63], v[150:153], v[166:169], v[60:63]
	v_mfma_f32_16x16x32_bf16 v[56:59], v[158:161], v[166:169], v[56:59]
	v_mfma_f32_16x16x32_bf16 v[44:47], v[150:153], v[174:177], v[44:47]
	v_mfma_f32_16x16x32_bf16 v[40:43], v[158:161], v[174:177], v[40:43]
	v_mfma_f32_16x16x32_bf16 v[28:31], v[150:153], v[182:185], v[28:31]
	v_mfma_f32_16x16x32_bf16 v[24:27], v[158:161], v[182:185], v[24:27]
	v_mfma_f32_16x16x32_bf16 v[12:15], v[150:153], v[190:193], v[12:15]
	v_mfma_f32_16x16x32_bf16 v[8:11], v[158:161], v[190:193], v[8:11]
	s_setprio 0
	s_barrier
	s_add_u32 s72, s58, 0x40000
	s_addc_u32 s73, s59, 0
	s_add_i32 s26, s65, s22
	v_lshl_add_u64 v[146:147], s[72:73], 0, v[128:129]
	s_mov_b32 m0, s26
	s_nop 0
	global_load_lds_dwordx4 v[146:147], off
	v_lshl_add_u64 v[146:147], s[72:73], 0, v[130:131]
	s_add_i32 m0, s26, 0x2000
	s_nop 0
	global_load_lds_dwordx4 v[146:147], off
	s_waitcnt vmcnt(6)
	s_barrier
	s_setprio 1
	v_mfma_f32_16x16x32_bf16 v[52:55], v[194:197], v[162:165], v[52:55]
	v_mfma_f32_16x16x32_bf16 v[48:51], v[210:213], v[162:165], v[48:51]
	v_mfma_f32_16x16x32_bf16 v[36:39], v[194:197], v[170:173], v[36:39]
	v_mfma_f32_16x16x32_bf16 v[32:35], v[210:213], v[170:173], v[32:35]
	v_mfma_f32_16x16x32_bf16 v[20:23], v[194:197], v[178:181], v[20:23]
	v_mfma_f32_16x16x32_bf16 v[16:19], v[210:213], v[178:181], v[16:19]
	v_mfma_f32_16x16x32_bf16 v[4:7], v[194:197], v[186:189], v[4:7]
	v_mfma_f32_16x16x32_bf16 v[0:3], v[210:213], v[186:189], v[0:3]
	v_mfma_f32_16x16x32_bf16 v[52:55], v[198:201], v[166:169], v[52:55]
	v_mfma_f32_16x16x32_bf16 v[48:51], v[214:217], v[166:169], v[48:51]
	v_mfma_f32_16x16x32_bf16 v[36:39], v[198:201], v[174:177], v[36:39]
	v_mfma_f32_16x16x32_bf16 v[32:35], v[214:217], v[174:177], v[32:35]
	v_mfma_f32_16x16x32_bf16 v[20:23], v[198:201], v[182:185], v[20:23]
	v_mfma_f32_16x16x32_bf16 v[16:19], v[214:217], v[182:185], v[16:19]
	v_mfma_f32_16x16x32_bf16 v[4:7], v[198:201], v[190:193], v[4:7]
	v_mfma_f32_16x16x32_bf16 v[0:3], v[214:217], v[190:193], v[0:3]
	s_setprio 0
	s_add_i32 s26, 0, 0x18000
	v_add_u32_e32 v158, s26, v144
	s_barrier
	ds_read_b128 v[146:149], v158
	ds_read_b128 v[150:153], v158 offset:1024
	ds_read_b128 v[154:157], v158 offset:2048
	ds_read_b128 v[158:161], v158 offset:3072
	s_add_u32 s60, s60, 0x40000
	s_addc_u32 s61, s61, 0
	s_mov_b32 m0, s24
	v_lshl_add_u64 v[194:195], s[60:61], 0, v[128:129]
	ds_read_b128 v[162:165], v145 offset:32768
	ds_read_b128 v[166:169], v145 offset:33792
	ds_read_b128 v[170:173], v145 offset:34816
	ds_read_b128 v[174:177], v145 offset:35840
	ds_read_b128 v[178:181], v145 offset:36864
	ds_read_b128 v[182:185], v145 offset:37888
	ds_read_b128 v[186:189], v145 offset:38912
	ds_read_b128 v[190:193], v145 offset:39936
	global_load_lds_dwordx4 v[194:195], off
	v_lshl_add_u64 v[194:195], s[60:61], 0, v[130:131]
	s_mov_b32 m0, s25
	s_nop 0
	global_load_lds_dwordx4 v[194:195], off
	s_waitcnt lgkmcnt(8)
	s_barrier
	s_waitcnt lgkmcnt(0)
	s_setprio 1
	s_waitcnt lgkmcnt(0)
	v_mfma_f32_16x16x32_bf16 v[124:127], v[146:149], v[162:165], v[124:127]
	v_mfma_f32_16x16x32_bf16 v[120:123], v[154:157], v[162:165], v[120:123]
	v_mfma_f32_16x16x32_bf16 v[108:111], v[146:149], v[170:173], v[108:111]
	v_mfma_f32_16x16x32_bf16 v[104:107], v[154:157], v[170:173], v[104:107]
	v_mfma_f32_16x16x32_bf16 v[92:95], v[146:149], v[178:181], v[92:95]
	v_mfma_f32_16x16x32_bf16 v[88:91], v[154:157], v[178:181], v[88:91]
	v_mfma_f32_16x16x32_bf16 v[76:79], v[146:149], v[186:189], v[76:79]
	v_mfma_f32_16x16x32_bf16 v[72:75], v[154:157], v[186:189], v[72:75]
	v_mfma_f32_16x16x32_bf16 v[124:127], v[150:153], v[166:169], v[124:127]
	v_mfma_f32_16x16x32_bf16 v[120:123], v[158:161], v[166:169], v[120:123]
	v_mfma_f32_16x16x32_bf16 v[108:111], v[150:153], v[174:177], v[108:111]
	v_mfma_f32_16x16x32_bf16 v[104:107], v[158:161], v[174:177], v[104:107]
	v_mfma_f32_16x16x32_bf16 v[92:95], v[150:153], v[182:185], v[92:95]
	v_mfma_f32_16x16x32_bf16 v[88:91], v[158:161], v[182:185], v[88:91]
	v_mfma_f32_16x16x32_bf16 v[76:79], v[150:153], v[190:193], v[76:79]
	v_mfma_f32_16x16x32_bf16 v[72:75], v[158:161], v[190:193], v[72:75]
	s_setprio 0
	s_barrier
	s_add_i32 s27, 0, 0x1c000
	s_add_i32 s26, s26, s22
	v_add_u32_e32 v209, s27, v144
	v_lshl_add_u64 v[218:219], v[218:219], 0, s[8:9]
	s_mov_b32 m0, s26
	ds_read_b128 v[194:197], v209
	ds_read_b128 v[198:201], v209 offset:1024
	ds_read_b128 v[210:213], v209 offset:2048
	ds_read_b128 v[214:217], v209 offset:3072
	global_load_lds_dwordx4 v[218:219], off
	v_lshl_add_u64 v[218:219], v[220:221], 0, s[8:9]
	s_add_i32 m0, s26, 0x2000
	s_nop 0
	global_load_lds_dwordx4 v[218:219], off
	s_barrier
	s_waitcnt lgkmcnt(0)
	s_setprio 1
	s_waitcnt lgkmcnt(0)
	v_mfma_f32_16x16x32_bf16 v[116:119], v[194:197], v[162:165], v[116:119]
	v_mfma_f32_16x16x32_bf16 v[112:115], v[210:213], v[162:165], v[112:115]
	v_mfma_f32_16x16x32_bf16 v[100:103], v[194:197], v[170:173], v[100:103]
	v_mfma_f32_16x16x32_bf16 v[96:99], v[210:213], v[170:173], v[96:99]
	v_mfma_f32_16x16x32_bf16 v[84:87], v[194:197], v[178:181], v[84:87]
	v_mfma_f32_16x16x32_bf16 v[80:83], v[210:213], v[178:181], v[80:83]
	v_mfma_f32_16x16x32_bf16 v[68:71], v[194:197], v[186:189], v[68:71]
	v_mfma_f32_16x16x32_bf16 v[64:67], v[210:213], v[186:189], v[64:67]
	v_mfma_f32_16x16x32_bf16 v[116:119], v[198:201], v[166:169], v[116:119]
	v_mfma_f32_16x16x32_bf16 v[112:115], v[214:217], v[166:169], v[112:115]
	v_mfma_f32_16x16x32_bf16 v[100:103], v[198:201], v[174:177], v[100:103]
	v_mfma_f32_16x16x32_bf16 v[96:99], v[214:217], v[174:177], v[96:99]
	v_mfma_f32_16x16x32_bf16 v[84:87], v[198:201], v[182:185], v[84:87]
	v_mfma_f32_16x16x32_bf16 v[80:83], v[214:217], v[182:185], v[80:83]
	v_mfma_f32_16x16x32_bf16 v[68:71], v[198:201], v[190:193], v[68:71]
	v_mfma_f32_16x16x32_bf16 v[64:67], v[214:217], v[190:193], v[64:67]
	s_setprio 0
	s_mov_b32 m0, s33
	v_lshl_add_u64 v[218:219], v[222:223], 0, s[8:9]
	s_barrier
	ds_read_b128 v[162:165], v145 offset:49152
	ds_read_b128 v[166:169], v145 offset:50176
	ds_read_b128 v[170:173], v145 offset:51200
	ds_read_b128 v[174:177], v145 offset:52224
	ds_read_b128 v[178:181], v145 offset:53248
	ds_read_b128 v[182:185], v145 offset:54272
	ds_read_b128 v[186:189], v145 offset:55296
	ds_read_b128 v[190:193], v145 offset:56320
	global_load_lds_dwordx4 v[218:219], off
	v_lshl_add_u64 v[218:219], v[224:225], 0, s[8:9]
	s_mov_b32 m0, s62
	s_nop 0
	global_load_lds_dwordx4 v[218:219], off
	s_barrier
	s_waitcnt lgkmcnt(0)
	s_setprio 1
	s_waitcnt lgkmcnt(0)
	v_mfma_f32_16x16x32_bf16 v[60:63], v[146:149], v[162:165], v[60:63]
	v_mfma_f32_16x16x32_bf16 v[56:59], v[154:157], v[162:165], v[56:59]
	v_mfma_f32_16x16x32_bf16 v[44:47], v[146:149], v[170:173], v[44:47]
	v_mfma_f32_16x16x32_bf16 v[40:43], v[154:157], v[170:173], v[40:43]
	v_mfma_f32_16x16x32_bf16 v[28:31], v[146:149], v[178:181], v[28:31]
	v_mfma_f32_16x16x32_bf16 v[24:27], v[154:157], v[178:181], v[24:27]
	v_mfma_f32_16x16x32_bf16 v[12:15], v[146:149], v[186:189], v[12:15]
	v_mfma_f32_16x16x32_bf16 v[8:11], v[154:157], v[186:189], v[8:11]
	v_mfma_f32_16x16x32_bf16 v[60:63], v[150:153], v[166:169], v[60:63]
	v_mfma_f32_16x16x32_bf16 v[56:59], v[158:161], v[166:169], v[56:59]
	v_mfma_f32_16x16x32_bf16 v[44:47], v[150:153], v[174:177], v[44:47]
	v_mfma_f32_16x16x32_bf16 v[40:43], v[158:161], v[174:177], v[40:43]
	v_mfma_f32_16x16x32_bf16 v[28:31], v[150:153], v[182:185], v[28:31]
	v_mfma_f32_16x16x32_bf16 v[24:27], v[158:161], v[182:185], v[24:27]
	v_mfma_f32_16x16x32_bf16 v[12:15], v[150:153], v[190:193], v[12:15]
	v_mfma_f32_16x16x32_bf16 v[8:11], v[158:161], v[190:193], v[8:11]
	s_setprio 0
	s_barrier
	s_add_u32 s58, s58, 0x40080
	s_addc_u32 s59, s59, 0
	s_add_i32 s26, s27, s22
	v_lshl_add_u64 v[146:147], s[58:59], 0, v[128:129]
	s_mov_b32 m0, s26
	s_nop 0
	global_load_lds_dwordx4 v[146:147], off
	v_lshl_add_u64 v[146:147], s[58:59], 0, v[130:131]
	s_add_i32 m0, s26, 0x2000
	s_nop 0
	global_load_lds_dwordx4 v[146:147], off
	s_waitcnt vmcnt(6)
	s_barrier
	s_setprio 1
	v_mfma_f32_16x16x32_bf16 v[52:55], v[194:197], v[162:165], v[52:55]
	v_mfma_f32_16x16x32_bf16 v[48:51], v[210:213], v[162:165], v[48:51]
	v_mfma_f32_16x16x32_bf16 v[36:39], v[194:197], v[170:173], v[36:39]
	v_mfma_f32_16x16x32_bf16 v[32:35], v[210:213], v[170:173], v[32:35]
	v_mfma_f32_16x16x32_bf16 v[20:23], v[194:197], v[178:181], v[20:23]
	v_mfma_f32_16x16x32_bf16 v[16:19], v[210:213], v[178:181], v[16:19]
	v_mfma_f32_16x16x32_bf16 v[4:7], v[194:197], v[186:189], v[4:7]
	v_mfma_f32_16x16x32_bf16 v[0:3], v[210:213], v[186:189], v[0:3]
	v_mfma_f32_16x16x32_bf16 v[52:55], v[198:201], v[166:169], v[52:55]
	v_mfma_f32_16x16x32_bf16 v[48:51], v[214:217], v[166:169], v[48:51]
	v_mfma_f32_16x16x32_bf16 v[36:39], v[198:201], v[174:177], v[36:39]
	v_mfma_f32_16x16x32_bf16 v[32:35], v[214:217], v[174:177], v[32:35]
	v_mfma_f32_16x16x32_bf16 v[20:23], v[198:201], v[182:185], v[20:23]
	v_mfma_f32_16x16x32_bf16 v[16:19], v[214:217], v[182:185], v[16:19]
	v_mfma_f32_16x16x32_bf16 v[4:7], v[198:201], v[190:193], v[4:7]
	v_mfma_f32_16x16x32_bf16 v[0:3], v[214:217], v[190:193], v[0:3]
	s_setprio 0
	s_add_i32 s71, s71, 2
	s_add_u32 s56, s56, 0x100
	s_addc_u32 s57, s57, 0
	s_cmp_gt_u32 s71, 13
	s_barrier
	s_cbranch_scc0 .LBB0_898
	s_mov_b64 s[98:99], exec
	v_readlane_b32 s100, v234, 18
	v_readlane_b32 s101, v234, 19
	v_mov_b32_e32 v242, 1
	s_mov_b64 exec, s[100:101]
	s_cbranch_execz .Lxs_skip
	global_atomic_add v[244:245], v242, off offset:516
.Lxs_skip:
	s_mov_b64 exec, s[98:99]
	s_add_u32 s56, s67, 0xffffff00
	s_addc_u32 s57, s68, -1
	s_andn2_b64 vcc, exec, s[4:5]
	s_cbranch_vccnz .LBB0_889
	v_mov_b32_e32 v0, 0
	s_mov_b32 s13, s14
	s_mov_b32 s2, s16
	s_mov_b64 s[6:7], s[38:39]
	s_mov_b32 s63, s66
	v_mov_b32_e32 v1, v0
	v_mov_b32_e32 v2, v0
	v_mov_b32_e32 v3, v0
	v_mov_b32_e32 v4, v0
	v_mov_b32_e32 v5, v0
	v_mov_b32_e32 v6, v0
	v_mov_b32_e32 v7, v0
	v_mov_b32_e32 v16, v0
	v_mov_b32_e32 v17, v0
	v_mov_b32_e32 v18, v0
	v_mov_b32_e32 v19, v0
	v_mov_b32_e32 v20, v0
	v_mov_b32_e32 v21, v0
	v_mov_b32_e32 v22, v0
	v_mov_b32_e32 v23, v0
	v_mov_b32_e32 v32, v0
	v_mov_b32_e32 v33, v0
	v_mov_b32_e32 v34, v0
	v_mov_b32_e32 v35, v0
	v_mov_b32_e32 v36, v0
	v_mov_b32_e32 v37, v0
	v_mov_b32_e32 v38, v0
	v_mov_b32_e32 v39, v0
	v_mov_b32_e32 v48, v0
	v_mov_b32_e32 v49, v0
	v_mov_b32_e32 v50, v0
	v_mov_b32_e32 v51, v0
	v_mov_b32_e32 v52, v0
	v_mov_b32_e32 v53, v0
	v_mov_b32_e32 v54, v0
	v_mov_b32_e32 v55, v0
	v_mov_b32_e32 v8, v0
	v_mov_b32_e32 v9, v0
	v_mov_b32_e32 v10, v0
	v_mov_b32_e32 v11, v0
	v_mov_b32_e32 v12, v0
	v_mov_b32_e32 v13, v0
	v_mov_b32_e32 v14, v0
	v_mov_b32_e32 v15, v0
	v_mov_b32_e32 v24, v0
	v_mov_b32_e32 v25, v0
	v_mov_b32_e32 v26, v0
	v_mov_b32_e32 v27, v0
	v_mov_b32_e32 v28, v0
	v_mov_b32_e32 v29, v0
	v_mov_b32_e32 v30, v0
	v_mov_b32_e32 v31, v0
	v_mov_b32_e32 v40, v0
	v_mov_b32_e32 v41, v0
	v_mov_b32_e32 v42, v0
	v_mov_b32_e32 v43, v0
	v_mov_b32_e32 v44, v0
	v_mov_b32_e32 v45, v0
	v_mov_b32_e32 v46, v0
	v_mov_b32_e32 v47, v0
	v_mov_b32_e32 v56, v0
	v_mov_b32_e32 v57, v0
	v_mov_b32_e32 v58, v0
	v_mov_b32_e32 v59, v0
	v_mov_b32_e32 v60, v0
	v_mov_b32_e32 v61, v0
	v_mov_b32_e32 v62, v0
	v_mov_b32_e32 v63, v0
	v_mov_b32_e32 v64, v0
	v_mov_b32_e32 v65, v0
	v_mov_b32_e32 v66, v0
	v_mov_b32_e32 v67, v0
	v_mov_b32_e32 v68, v0
	v_mov_b32_e32 v69, v0
	v_mov_b32_e32 v70, v0
	v_mov_b32_e32 v71, v0
	v_mov_b32_e32 v80, v0
	v_mov_b32_e32 v81, v0
	v_mov_b32_e32 v82, v0
	v_mov_b32_e32 v83, v0
	v_mov_b32_e32 v84, v0
	v_mov_b32_e32 v85, v0
	v_mov_b32_e32 v86, v0
	v_mov_b32_e32 v87, v0
	v_mov_b32_e32 v96, v0
	v_mov_b32_e32 v97, v0
	v_mov_b32_e32 v98, v0
	v_mov_b32_e32 v99, v0
	v_mov_b32_e32 v100, v0
	v_mov_b32_e32 v101, v0
	v_mov_b32_e32 v102, v0
	v_mov_b32_e32 v103, v0
	v_mov_b32_e32 v112, v0
	v_mov_b32_e32 v113, v0
	v_mov_b32_e32 v114, v0
	v_mov_b32_e32 v115, v0
	v_mov_b32_e32 v116, v0
	v_mov_b32_e32 v117, v0
	v_mov_b32_e32 v118, v0
	v_mov_b32_e32 v119, v0
	v_mov_b32_e32 v72, v0
	v_mov_b32_e32 v73, v0
	v_mov_b32_e32 v74, v0
	v_mov_b32_e32 v75, v0
	v_mov_b32_e32 v76, v0
	v_mov_b32_e32 v77, v0
	v_mov_b32_e32 v78, v0
	v_mov_b32_e32 v79, v0
	v_mov_b32_e32 v88, v0
	v_mov_b32_e32 v89, v0
	v_mov_b32_e32 v90, v0
	v_mov_b32_e32 v91, v0
	v_mov_b32_e32 v92, v0
	v_mov_b32_e32 v93, v0
	v_mov_b32_e32 v94, v0
	v_mov_b32_e32 v95, v0
	v_mov_b32_e32 v104, v0
	v_mov_b32_e32 v105, v0
	v_mov_b32_e32 v106, v0
	v_mov_b32_e32 v107, v0
	v_mov_b32_e32 v108, v0
	v_mov_b32_e32 v109, v0
	v_mov_b32_e32 v110, v0
	v_mov_b32_e32 v111, v0
	v_mov_b32_e32 v120, v0
	v_mov_b32_e32 v121, v0
	v_mov_b32_e32 v122, v0
	v_mov_b32_e32 v123, v0
	v_mov_b32_e32 v124, v0
	v_mov_b32_e32 v125, v0
	v_mov_b32_e32 v126, v0
	v_mov_b32_e32 v127, v0
	s_andn2_b64 vcc, exec, s[0:1]
	s_cbranch_vccnz .LBB0_890

.LBB0_903:
	s_barrier
	s_add_u32 s0, s78, 0xedc8000
	v_ashrrev_i32_e32 v190, 6, v202
	s_addc_u32 s1, s79, 0
	v_readfirstlane_b32 s3, v190
	s_and_b32 s6, s3, 3
	s_lshl_b32 s4, s13, 8
	s_lshl_b32 s5, s6, 5
	s_or_b32 s4, s5, s4
	v_lshrrev_b32_e32 v128, 2, v202
	v_and_or_b32 v188, v128, 12, s4
	s_lshl_b32 s4, s2, 7
	s_and_b32 s4, s4, 0xfffffc00
	s_ashr_i32 s5, s4, 31
	s_lshl_b64 s[4:5], s[4:5], 2
	v_readlane_b32 s7, v234, 21
	s_add_u32 s4, s7, s4
	v_readlane_b32 s7, v234, 20
	s_addc_u32 s5, s7, s5
	s_lshl_b32 s3, s3, 4
	s_andn2_b32 s3, s3, 63
	v_and_or_b32 v128, v202, 15, s3
	v_lshl_add_u32 v172, s2, 8, v128
	v_readlane_b32 s56, v234, 0
	v_ashrrev_i32_e32 v173, 31, v172
	v_readlane_b32 s57, v234, 1
	v_ashrrev_i32_e32 v189, 31, v188
	v_lshlrev_b64 v[146:147], 12, v[172:173]
	s_mov_b64 s[16:17], s[56:57]
	v_lshlrev_b64 v[144:145], 2, v[188:189]
	v_lshl_add_u64 v[128:129], s[16:17], 0, v[146:147]
	v_lshl_add_u64 v[136:137], s[4:5], 0, v[144:145]
	v_lshl_add_u64 v[160:161], v[128:129], 0, v[144:145]
	global_load_dwordx4 v[148:151], v[160:161], off
	global_load_dwordx4 v[132:135], v[136:137], off
	global_load_dwordx4 v[128:131], v[136:137], off offset:64
	global_load_dwordx4 v[152:155], v[160:161], off offset:64
	global_load_dwordx4 v[156:159], v[160:161], off offset:512
	global_load_dwordx4 v[140:143], v[136:137], off offset:512
	s_nop 0
	global_load_dwordx4 v[136:139], v[136:137], off offset:576
	s_nop 0
	global_load_dwordx4 v[160:163], v[160:161], off offset:576
	v_and_b32_e32 v191, 63, v202
	v_cmp_gt_u32_e32 vcc, 16, v191
	s_mov_b32 s5, 0
	v_lshlrev_b64 v[174:175], 6, v[172:173]
	v_readlane_b32 s58, v234, 2
	v_readlane_b32 s59, v234, 3
	v_readlane_b32 s60, v234, 4
	v_readlane_b32 s61, v234, 5
	v_readlane_b32 s62, v234, 6
	v_readlane_b32 s63, v234, 7
	v_readlane_b32 s64, v234, 8
	v_readlane_b32 s65, v234, 9
	v_readlane_b32 s66, v234, 10
	v_readlane_b32 s67, v234, 11
	v_readlane_b32 s68, v234, 12
	v_readlane_b32 s69, v234, 13
	v_readlane_b32 s70, v234, 14
	v_readlane_b32 s71, v234, 15
	s_waitcnt vmcnt(0)
	v_pk_fma_f32 v[126:127], v[126:127], v[134:135], v[150:151]
	v_pk_fma_f32 v[124:125], v[124:125], v[132:133], v[148:149]
	v_pk_fma_f32 v[122:123], v[122:123], v[130:131], v[154:155]
	v_pk_fma_f32 v[120:121], v[120:121], v[128:129], v[152:153]
	v_pk_fma_f32 v[118:119], v[118:119], v[142:143], v[158:159]
	v_pk_fma_f32 v[116:117], v[116:117], v[140:141], v[156:157]
	v_mul_f32_e32 v148, v125, v125
	v_mul_f32_e32 v149, v127, v127
	v_mul_f32_e32 v150, v121, v121
	v_mul_f32_e32 v151, v123, v123
	v_pk_fma_f32 v[114:115], v[114:115], v[138:139], v[162:163]
	v_pk_fma_f32 v[112:113], v[112:113], v[136:137], v[160:161]
	v_mul_f32_e32 v152, v117, v117
	v_mul_f32_e32 v153, v119, v119
	v_fmac_f32_e32 v148, v124, v124
	v_fmac_f32_e32 v149, v126, v126
	v_fmac_f32_e32 v150, v120, v120
	v_fmac_f32_e32 v151, v122, v122
	v_mul_f32_e32 v154, v113, v113
	v_mul_f32_e32 v155, v115, v115
	v_fmac_f32_e32 v152, v116, v116
	v_fmac_f32_e32 v153, v118, v118
	v_add_f32_e32 v148, v148, v149
	v_add_f32_e32 v149, v150, v151
	v_fmac_f32_e32 v154, v112, v112
	v_fmac_f32_e32 v155, v114, v114
	v_add_f32_e32 v150, v152, v153
	v_add_f32_e32 v148, v148, v149
	v_add_f32_e32 v148, v148, v150
	v_add_f32_e32 v149, v154, v155
	v_add_f32_e32 v148, v148, v149
	ds_bpermute_b32 v149, v207, v148
	s_waitcnt lgkmcnt(0)
	v_add_f32_e32 v148, v148, v149
	ds_bpermute_b32 v149, v208, v148
	s_and_saveexec_b64 s[2:3], vcc
	v_readlane_b32 s24, v234, 45
	v_readlane_b32 s14, v234, 49
	v_readlane_b32 s25, v234, 46
	v_readlane_b32 s15, v234, 50
	s_cbranch_execz .LBB0_905
	s_lshl_b32 s8, s13, 2
	s_waitcnt lgkmcnt(0)
	v_add_f32_e32 v150, v148, v149
	s_ashr_i32 s9, s8, 31
	v_lshl_add_u64 v[148:149], s[0:1], 0, v[174:175]
	v_lshl_add_u64 v[148:149], s[8:9], 2, v[148:149]
	s_lshl_b32 s4, s6, 2
	v_lshl_add_u64 v[148:149], v[148:149], 0, s[4:5]
	global_store_dword v[148:149], v150, off sc1
.LBB0_905:
	s_or_b64 exec, exec, s[2:3]
	v_or_b32_e32 v166, 16, v172
	v_ashrrev_i32_e32 v167, 31, v166
	s_waitcnt lgkmcnt(0)
	v_lshlrev_b64 v[148:149], 12, v[166:167]
	v_lshl_add_u64 v[150:151], s[16:17], 0, v[148:149]
	v_lshl_add_u64 v[162:163], v[188:189], 2, v[150:151]
	global_load_dwordx4 v[150:153], v[162:163], off
	global_load_dwordx4 v[154:157], v[162:163], off offset:64
	global_load_dwordx4 v[158:161], v[162:163], off offset:512
	s_nop 0
	global_load_dwordx4 v[162:165], v[162:163], off offset:576
	v_lshlrev_b64 v[176:177], 6, v[166:167]
	s_waitcnt vmcnt(3)
	v_pk_fma_f32 v[110:111], v[110:111], v[134:135], v[152:153]
	v_pk_fma_f32 v[108:109], v[108:109], v[132:133], v[150:151]
	s_waitcnt vmcnt(2)
	v_pk_fma_f32 v[106:107], v[106:107], v[130:131], v[156:157]
	v_pk_fma_f32 v[104:105], v[104:105], v[128:129], v[154:155]
	s_waitcnt vmcnt(1)
	v_pk_fma_f32 v[102:103], v[102:103], v[142:143], v[160:161]
	v_pk_fma_f32 v[100:101], v[100:101], v[140:141], v[158:159]
	v_mul_f32_e32 v150, v109, v109
	v_mul_f32_e32 v151, v111, v111
	v_mul_f32_e32 v152, v105, v105
	v_mul_f32_e32 v153, v107, v107
	s_waitcnt vmcnt(0)
	v_pk_fma_f32 v[98:99], v[98:99], v[138:139], v[164:165]
	v_pk_fma_f32 v[96:97], v[96:97], v[136:137], v[162:163]
	v_mul_f32_e32 v154, v101, v101
	v_mul_f32_e32 v155, v103, v103
	v_fmac_f32_e32 v150, v108, v108
	v_fmac_f32_e32 v151, v110, v110
	v_fmac_f32_e32 v152, v104, v104
	v_fmac_f32_e32 v153, v106, v106
	v_mul_f32_e32 v156, v97, v97
	v_mul_f32_e32 v157, v99, v99
	v_fmac_f32_e32 v154, v100, v100
	v_fmac_f32_e32 v155, v102, v102
	v_add_f32_e32 v150, v150, v151
	v_add_f32_e32 v151, v152, v153
	v_fmac_f32_e32 v156, v96, v96
	v_fmac_f32_e32 v157, v98, v98
	v_add_f32_e32 v152, v154, v155
	v_add_f32_e32 v150, v150, v151
	v_add_f32_e32 v150, v150, v152
	v_add_f32_e32 v151, v156, v157
	v_add_f32_e32 v150, v150, v151
	ds_bpermute_b32 v151, v207, v150
	s_waitcnt lgkmcnt(0)
	v_add_f32_e32 v150, v150, v151
	ds_bpermute_b32 v151, v208, v150
	s_and_saveexec_b64 s[2:3], vcc
	s_cbranch_execz .LBB0_907
	s_lshl_b32 s4, s13, 2
	s_waitcnt lgkmcnt(0)
	v_add_f32_e32 v152, v150, v151
	s_ashr_i32 s5, s4, 31
	v_lshl_add_u64 v[150:151], s[0:1], 0, v[176:177]
	v_lshl_add_u64 v[150:151], s[4:5], 2, v[150:151]
	s_lshl_b32 s4, s6, 2
	s_mov_b32 s5, 0
	v_lshl_add_u64 v[150:151], v[150:151], 0, s[4:5]
	global_store_dword v[150:151], v152, off sc1
.LBB0_907:
	s_or_b64 exec, exec, s[2:3]
	v_or_b32_e32 v168, 32, v172
	v_ashrrev_i32_e32 v169, 31, v168
	s_waitcnt lgkmcnt(0)
	v_lshlrev_b64 v[150:151], 12, v[168:169]
	v_lshl_add_u64 v[152:153], s[16:17], 0, v[150:151]
	v_lshl_add_u64 v[164:165], v[188:189], 2, v[152:153]
	global_load_dwordx4 v[152:155], v[164:165], off
	global_load_dwordx4 v[156:159], v[164:165], off offset:64
	global_load_dwordx4 v[160:163], v[164:165], off offset:512
	s_nop 0
	global_load_dwordx4 v[164:167], v[164:165], off offset:576
	v_lshlrev_b64 v[178:179], 6, v[168:169]
	s_waitcnt vmcnt(3)
	v_pk_fma_f32 v[94:95], v[94:95], v[134:135], v[154:155]
	v_pk_fma_f32 v[92:93], v[92:93], v[132:133], v[152:153]
	s_waitcnt vmcnt(2)
	v_pk_fma_f32 v[90:91], v[90:91], v[130:131], v[158:159]
	v_pk_fma_f32 v[88:89], v[88:89], v[128:129], v[156:157]
	s_waitcnt vmcnt(1)
	v_pk_fma_f32 v[86:87], v[86:87], v[142:143], v[162:163]
	v_pk_fma_f32 v[84:85], v[84:85], v[140:141], v[160:161]
	v_mul_f32_e32 v152, v93, v93
	v_mul_f32_e32 v153, v95, v95
	v_mul_f32_e32 v154, v89, v89
	v_mul_f32_e32 v155, v91, v91
	s_waitcnt vmcnt(0)
	v_pk_fma_f32 v[82:83], v[82:83], v[138:139], v[166:167]
	v_pk_fma_f32 v[80:81], v[80:81], v[136:137], v[164:165]
	v_mul_f32_e32 v156, v85, v85
	v_mul_f32_e32 v157, v87, v87
	v_fmac_f32_e32 v152, v92, v92
	v_fmac_f32_e32 v153, v94, v94
	v_fmac_f32_e32 v154, v88, v88
	v_fmac_f32_e32 v155, v90, v90
	v_mul_f32_e32 v158, v81, v81
	v_mul_f32_e32 v159, v83, v83
	v_fmac_f32_e32 v156, v84, v84
	v_fmac_f32_e32 v157, v86, v86
	v_add_f32_e32 v152, v152, v153
	v_add_f32_e32 v153, v154, v155
	v_fmac_f32_e32 v158, v80, v80
	v_fmac_f32_e32 v159, v82, v82
	v_add_f32_e32 v154, v156, v157
	v_add_f32_e32 v152, v152, v153
	v_add_f32_e32 v152, v152, v154
	v_add_f32_e32 v153, v158, v159
	v_add_f32_e32 v152, v152, v153
	ds_bpermute_b32 v153, v207, v152
	s_waitcnt lgkmcnt(0)
	v_add_f32_e32 v152, v152, v153
	ds_bpermute_b32 v153, v208, v152
	s_and_saveexec_b64 s[2:3], vcc
	s_cbranch_execz .LBB0_909
	s_lshl_b32 s4, s13, 2
	s_waitcnt lgkmcnt(0)
	v_add_f32_e32 v154, v152, v153
	s_ashr_i32 s5, s4, 31
	v_lshl_add_u64 v[152:153], s[0:1], 0, v[178:179]
	v_lshl_add_u64 v[152:153], s[4:5], 2, v[152:153]
	s_lshl_b32 s4, s6, 2
	s_mov_b32 s5, 0
	v_lshl_add_u64 v[152:153], v[152:153], 0, s[4:5]
	global_store_dword v[152:153], v154, off sc1
.LBB0_909:
	s_or_b64 exec, exec, s[2:3]
	v_or_b32_e32 v170, 48, v172
	v_ashrrev_i32_e32 v171, 31, v170
	s_waitcnt lgkmcnt(0)
	v_lshlrev_b64 v[152:153], 12, v[170:171]
	v_lshl_add_u64 v[154:155], s[16:17], 0, v[152:153]
	v_lshl_add_u64 v[166:167], v[188:189], 2, v[154:155]
	global_load_dwordx4 v[154:157], v[166:167], off
	global_load_dwordx4 v[158:161], v[166:167], off offset:64
	global_load_dwordx4 v[162:165], v[166:167], off offset:512
	s_nop 0
	global_load_dwordx4 v[166:169], v[166:167], off offset:576
	v_lshlrev_b64 v[180:181], 6, v[170:171]
	s_waitcnt vmcnt(3)
	v_pk_fma_f32 v[78:79], v[78:79], v[134:135], v[156:157]
	v_pk_fma_f32 v[76:77], v[76:77], v[132:133], v[154:155]
	s_waitcnt vmcnt(2)
	v_pk_fma_f32 v[74:75], v[74:75], v[130:131], v[160:161]
	v_pk_fma_f32 v[72:73], v[72:73], v[128:129], v[158:159]
	s_waitcnt vmcnt(1)
	v_pk_fma_f32 v[70:71], v[70:71], v[142:143], v[164:165]
	v_pk_fma_f32 v[68:69], v[68:69], v[140:141], v[162:163]
	v_mul_f32_e32 v154, v77, v77
	v_mul_f32_e32 v155, v79, v79
	v_mul_f32_e32 v156, v73, v73
	v_mul_f32_e32 v157, v75, v75
	s_waitcnt vmcnt(0)
	v_pk_fma_f32 v[66:67], v[66:67], v[138:139], v[168:169]
	v_pk_fma_f32 v[64:65], v[64:65], v[136:137], v[166:167]
	v_mul_f32_e32 v158, v69, v69
	v_mul_f32_e32 v159, v71, v71
	v_fmac_f32_e32 v154, v76, v76
	v_fmac_f32_e32 v155, v78, v78
	v_fmac_f32_e32 v156, v72, v72
	v_fmac_f32_e32 v157, v74, v74
	v_mul_f32_e32 v160, v65, v65
	v_mul_f32_e32 v161, v67, v67
	v_fmac_f32_e32 v158, v68, v68
	v_fmac_f32_e32 v159, v70, v70
	v_add_f32_e32 v154, v154, v155
	v_add_f32_e32 v155, v156, v157
	v_fmac_f32_e32 v160, v64, v64
	v_fmac_f32_e32 v161, v66, v66
	v_add_f32_e32 v156, v158, v159
	v_add_f32_e32 v154, v154, v155
	v_add_f32_e32 v154, v154, v156
	v_add_f32_e32 v155, v160, v161
	v_add_f32_e32 v154, v154, v155
	ds_bpermute_b32 v155, v207, v154
	s_waitcnt lgkmcnt(0)
	v_add_f32_e32 v154, v154, v155
	ds_bpermute_b32 v155, v208, v154
	s_and_saveexec_b64 s[2:3], vcc
	s_cbranch_execz .LBB0_911
	s_lshl_b32 s4, s13, 2
	s_waitcnt lgkmcnt(0)
	v_add_f32_e32 v156, v154, v155
	s_ashr_i32 s5, s4, 31
	v_lshl_add_u64 v[154:155], s[0:1], 0, v[180:181]
	v_lshl_add_u64 v[154:155], s[4:5], 2, v[154:155]
	s_lshl_b32 s4, s6, 2
	s_mov_b32 s5, 0
	v_lshl_add_u64 v[154:155], v[154:155], 0, s[4:5]
	global_store_dword v[154:155], v156, off sc1
.LBB0_911:
	s_or_b64 exec, exec, s[2:3]
	v_add_u32_e32 v182, 0x80, v172
	v_ashrrev_i32_e32 v183, 31, v182
	s_waitcnt lgkmcnt(0)
	v_lshlrev_b64 v[154:155], 12, v[182:183]
	v_lshl_add_u64 v[156:157], s[16:17], 0, v[154:155]
	v_lshl_add_u64 v[168:169], v[188:189], 2, v[156:157]
	global_load_dwordx4 v[156:159], v[168:169], off
	global_load_dwordx4 v[160:163], v[168:169], off offset:64
	global_load_dwordx4 v[164:167], v[168:169], off offset:512
	s_nop 0
	global_load_dwordx4 v[168:171], v[168:169], off offset:576
	v_lshlrev_b64 v[182:183], 6, v[182:183]
	s_waitcnt vmcnt(3)
	v_pk_fma_f32 v[62:63], v[62:63], v[134:135], v[158:159]
	v_pk_fma_f32 v[60:61], v[60:61], v[132:133], v[156:157]
	s_waitcnt vmcnt(2)
	v_pk_fma_f32 v[58:59], v[58:59], v[130:131], v[162:163]
	v_pk_fma_f32 v[56:57], v[56:57], v[128:129], v[160:161]
	s_waitcnt vmcnt(1)
	v_pk_fma_f32 v[54:55], v[54:55], v[142:143], v[166:167]
	v_pk_fma_f32 v[52:53], v[52:53], v[140:141], v[164:165]
	v_mul_f32_e32 v156, v61, v61
	v_mul_f32_e32 v157, v63, v63
	v_mul_f32_e32 v158, v57, v57
	v_mul_f32_e32 v159, v59, v59
	s_waitcnt vmcnt(0)
	v_pk_fma_f32 v[50:51], v[50:51], v[138:139], v[170:171]
	v_pk_fma_f32 v[48:49], v[48:49], v[136:137], v[168:169]
	v_mul_f32_e32 v160, v53, v53
	v_mul_f32_e32 v161, v55, v55
	v_fmac_f32_e32 v156, v60, v60
	v_fmac_f32_e32 v157, v62, v62
	v_fmac_f32_e32 v158, v56, v56
	v_fmac_f32_e32 v159, v58, v58
	v_mul_f32_e32 v162, v49, v49
	v_mul_f32_e32 v163, v51, v51
	v_fmac_f32_e32 v160, v52, v52
	v_fmac_f32_e32 v161, v54, v54
	v_add_f32_e32 v156, v156, v157
	v_add_f32_e32 v157, v158, v159
	v_fmac_f32_e32 v162, v48, v48
	v_fmac_f32_e32 v163, v50, v50
	v_add_f32_e32 v158, v160, v161
	v_add_f32_e32 v156, v156, v157
	v_add_f32_e32 v156, v156, v158
	v_add_f32_e32 v157, v162, v163
	v_add_f32_e32 v156, v156, v157
	ds_bpermute_b32 v157, v207, v156
	s_waitcnt lgkmcnt(0)
	v_add_f32_e32 v156, v156, v157
	ds_bpermute_b32 v157, v208, v156
	s_and_saveexec_b64 s[2:3], vcc
	s_cbranch_execz .LBB0_913
	s_lshl_b32 s4, s13, 2
	s_waitcnt lgkmcnt(0)
	v_add_f32_e32 v158, v156, v157
	s_ashr_i32 s5, s4, 31
	v_lshl_add_u64 v[156:157], s[0:1], 0, v[182:183]
	v_lshl_add_u64 v[156:157], s[4:5], 2, v[156:157]
	s_lshl_b32 s4, s6, 2
	s_mov_b32 s5, 0
	v_lshl_add_u64 v[156:157], v[156:157], 0, s[4:5]
	global_store_dword v[156:157], v158, off sc1
.LBB0_913:
	s_or_b64 exec, exec, s[2:3]
	v_add_u32_e32 v170, 0x90, v172
	v_ashrrev_i32_e32 v171, 31, v170
	s_waitcnt lgkmcnt(0)
	v_lshlrev_b64 v[156:157], 12, v[170:171]
	v_lshl_add_u64 v[158:159], s[16:17], 0, v[156:157]
	v_lshl_add_u64 v[184:185], v[188:189], 2, v[158:159]
	global_load_dwordx4 v[158:161], v[184:185], off
	global_load_dwordx4 v[162:165], v[184:185], off offset:64
	global_load_dwordx4 v[166:169], v[184:185], off offset:512
	s_nop 0
	global_load_dwordx4 v[184:187], v[184:185], off offset:576
	s_waitcnt vmcnt(3)
	v_pk_fma_f32 v[46:47], v[46:47], v[134:135], v[160:161]
	v_pk_fma_f32 v[44:45], v[44:45], v[132:133], v[158:159]
	s_waitcnt vmcnt(2)
	v_pk_fma_f32 v[42:43], v[42:43], v[130:131], v[164:165]
	v_pk_fma_f32 v[40:41], v[40:41], v[128:129], v[162:163]
	s_waitcnt vmcnt(1)
	v_pk_fma_f32 v[38:39], v[38:39], v[142:143], v[168:169]
	v_pk_fma_f32 v[36:37], v[36:37], v[140:141], v[166:167]
	v_mul_f32_e32 v158, v45, v45
	v_mul_f32_e32 v159, v47, v47
	v_mul_f32_e32 v160, v41, v41
	v_mul_f32_e32 v161, v43, v43
	s_waitcnt vmcnt(0)
	v_pk_fma_f32 v[34:35], v[34:35], v[138:139], v[186:187]
	v_pk_fma_f32 v[32:33], v[32:33], v[136:137], v[184:185]
	v_mul_f32_e32 v162, v37, v37
	v_mul_f32_e32 v163, v39, v39
	v_fmac_f32_e32 v158, v44, v44
	v_fmac_f32_e32 v159, v46, v46
	v_fmac_f32_e32 v160, v40, v40
	v_fmac_f32_e32 v161, v42, v42
	v_mul_f32_e32 v164, v33, v33
	v_mul_f32_e32 v165, v35, v35
	v_fmac_f32_e32 v162, v36, v36
	v_fmac_f32_e32 v163, v38, v38
	v_add_f32_e32 v158, v158, v159
	v_add_f32_e32 v159, v160, v161
	v_fmac_f32_e32 v164, v32, v32
	v_fmac_f32_e32 v165, v34, v34
	v_add_f32_e32 v160, v162, v163
	v_add_f32_e32 v158, v158, v159
	v_add_f32_e32 v158, v158, v160
	v_add_f32_e32 v159, v164, v165
	v_add_f32_e32 v158, v158, v159
	ds_bpermute_b32 v159, v207, v158
	v_lshlrev_b64 v[184:185], 6, v[170:171]
	s_waitcnt lgkmcnt(0)
	v_add_f32_e32 v158, v158, v159
	ds_bpermute_b32 v159, v208, v158
	s_and_saveexec_b64 s[2:3], vcc
	s_cbranch_execz .LBB0_915
	s_lshl_b32 s4, s13, 2
	s_waitcnt lgkmcnt(0)
	v_add_f32_e32 v160, v158, v159
	s_ashr_i32 s5, s4, 31
	v_lshl_add_u64 v[158:159], s[0:1], 0, v[184:185]
	v_lshl_add_u64 v[158:159], s[4:5], 2, v[158:159]
	s_lshl_b32 s4, s6, 2
	s_mov_b32 s5, 0
	v_lshl_add_u64 v[158:159], v[158:159], 0, s[4:5]
	global_store_dword v[158:159], v160, off sc1
.LBB0_915:
	s_or_b64 exec, exec, s[2:3]
	v_add_u32_e32 v186, 0xa0, v172
	v_ashrrev_i32_e32 v187, 31, v186
	s_waitcnt lgkmcnt(0)
	v_lshlrev_b64 v[158:159], 12, v[186:187]
	v_lshl_add_u64 v[160:161], s[16:17], 0, v[158:159]
	v_lshl_add_u64 v[160:161], v[188:189], 2, v[160:161]
	global_load_dwordx4 v[162:165], v[160:161], off
	global_load_dwordx4 v[168:171], v[160:161], off offset:64
	global_load_dwordx4 v[192:195], v[160:161], off offset:512
	global_load_dwordx4 v[196:199], v[160:161], off offset:576
	v_lshlrev_b64 v[186:187], 6, v[186:187]
	s_waitcnt vmcnt(3)
	v_pk_fma_f32 v[160:161], v[30:31], v[134:135], v[164:165]
	v_pk_fma_f32 v[166:167], v[28:29], v[132:133], v[162:163]
	s_waitcnt vmcnt(2)
	v_pk_fma_f32 v[30:31], v[26:27], v[130:131], v[170:171]
	v_pk_fma_f32 v[164:165], v[24:25], v[128:129], v[168:169]
	s_waitcnt vmcnt(1)
	v_pk_fma_f32 v[28:29], v[22:23], v[142:143], v[194:195]
	v_pk_fma_f32 v[162:163], v[20:21], v[140:141], v[192:193]
	s_waitcnt vmcnt(0)
	v_pk_fma_f32 v[168:169], v[18:19], v[138:139], v[198:199]
	v_pk_fma_f32 v[170:171], v[16:17], v[136:137], v[196:197]
	v_mul_f32_e32 v16, v167, v167
	v_mul_f32_e32 v17, v161, v161
	v_mul_f32_e32 v18, v165, v165
	v_mul_f32_e32 v19, v31, v31
	v_mul_f32_e32 v20, v163, v163
	v_mul_f32_e32 v21, v29, v29
	v_fmac_f32_e32 v16, v166, v166
	v_fmac_f32_e32 v17, v160, v160
	v_fmac_f32_e32 v18, v164, v164
	v_fmac_f32_e32 v19, v30, v30
	v_mul_f32_e32 v22, v171, v171
	v_mul_f32_e32 v23, v169, v169
	v_fmac_f32_e32 v20, v162, v162
	v_fmac_f32_e32 v21, v28, v28
	v_add_f32_e32 v16, v16, v17
	v_add_f32_e32 v17, v18, v19
	v_fmac_f32_e32 v22, v170, v170
	v_fmac_f32_e32 v23, v168, v168
	v_add_f32_e32 v18, v20, v21
	v_add_f32_e32 v16, v16, v17
	v_add_f32_e32 v16, v16, v18
	v_add_f32_e32 v17, v22, v23
	v_add_f32_e32 v16, v16, v17
	ds_bpermute_b32 v17, v207, v16
	s_waitcnt lgkmcnt(0)
	v_add_f32_e32 v16, v16, v17
	ds_bpermute_b32 v17, v208, v16
	s_and_saveexec_b64 s[2:3], vcc
	s_cbranch_execz .LBB0_917
	s_lshl_b32 s4, s13, 2
	s_waitcnt lgkmcnt(0)
	v_add_f32_e32 v18, v16, v17
	s_ashr_i32 s5, s4, 31
	v_lshl_add_u64 v[16:17], s[0:1], 0, v[186:187]
	v_lshl_add_u64 v[16:17], s[4:5], 2, v[16:17]
	s_lshl_b32 s4, s6, 2
	s_mov_b32 s5, 0
	v_lshl_add_u64 v[16:17], v[16:17], 0, s[4:5]
	global_store_dword v[16:17], v18, off sc1
.LBB0_917:
	s_or_b64 exec, exec, s[2:3]
	v_add_u32_e32 v200, 0xb0, v172
	v_ashrrev_i32_e32 v201, 31, v200
	v_lshlrev_b64 v[172:173], 12, v[200:201]
	s_waitcnt lgkmcnt(0)
	v_lshl_add_u64 v[16:17], s[16:17], 0, v[172:173]
	v_lshl_add_u64 v[20:21], v[188:189], 2, v[16:17]
	global_load_dwordx4 v[16:19], v[20:21], off
	global_load_dwordx4 v[22:25], v[20:21], off offset:64
	global_load_dwordx4 v[192:195], v[20:21], off offset:512
	global_load_dwordx4 v[196:199], v[20:21], off offset:576
	s_waitcnt vmcnt(3)
	v_pk_fma_f32 v[20:21], v[14:15], v[134:135], v[18:19]
	v_pk_fma_f32 v[26:27], v[12:13], v[132:133], v[16:17]
	s_waitcnt vmcnt(2)
	v_pk_fma_f32 v[18:19], v[10:11], v[130:131], v[24:25]
	v_pk_fma_f32 v[24:25], v[8:9], v[128:129], v[22:23]
	s_waitcnt vmcnt(1)
	v_pk_fma_f32 v[16:17], v[6:7], v[142:143], v[194:195]
	v_pk_fma_f32 v[22:23], v[4:5], v[140:141], v[192:193]
	s_waitcnt vmcnt(0)
	v_pk_fma_f32 v[128:129], v[2:3], v[138:139], v[198:199]
	v_pk_fma_f32 v[130:131], v[0:1], v[136:137], v[196:197]
	v_mul_f32_e32 v0, v27, v27
	v_mul_f32_e32 v1, v21, v21
	v_mul_f32_e32 v2, v25, v25
	v_mul_f32_e32 v3, v19, v19
	v_mul_f32_e32 v4, v23, v23
	v_mul_f32_e32 v5, v17, v17
	v_fmac_f32_e32 v0, v26, v26
	v_fmac_f32_e32 v1, v20, v20
	v_fmac_f32_e32 v2, v24, v24
	v_fmac_f32_e32 v3, v18, v18
	v_mul_f32_e32 v6, v131, v131
	v_mul_f32_e32 v7, v129, v129
	v_fmac_f32_e32 v4, v22, v22
	v_fmac_f32_e32 v5, v16, v16
	v_add_f32_e32 v0, v0, v1
	v_add_f32_e32 v1, v2, v3
	v_fmac_f32_e32 v6, v130, v130
	v_fmac_f32_e32 v7, v128, v128
	v_add_f32_e32 v2, v4, v5
	v_add_f32_e32 v0, v0, v1
	v_add_f32_e32 v0, v0, v2
	v_add_f32_e32 v1, v6, v7
	v_add_f32_e32 v0, v0, v1
	ds_bpermute_b32 v1, v207, v0
	v_lshlrev_b64 v[132:133], 6, v[200:201]
	s_waitcnt lgkmcnt(0)
	v_add_f32_e32 v0, v0, v1
	ds_bpermute_b32 v1, v208, v0
	s_and_saveexec_b64 s[2:3], vcc
	s_cbranch_execz .LBB0_919
	s_lshl_b32 s4, s13, 2
	s_waitcnt lgkmcnt(0)
	v_add_f32_e32 v2, v0, v1
	s_ashr_i32 s5, s4, 31
	v_lshl_add_u64 v[0:1], s[0:1], 0, v[132:133]
	v_lshl_add_u64 v[0:1], s[4:5], 2, v[0:1]
	s_lshl_b32 s4, s6, 2
	s_mov_b32 s5, 0
	v_lshl_add_u64 v[0:1], v[0:1], 0, s[4:5]
	global_store_dword v[0:1], v2, off sc1
.LBB0_919:
	s_or_b64 exec, exec, s[2:3]
	s_getreg_b32 s4, hwreg(HW_REG_XCC_ID, 0, 4)
	s_waitcnt vmcnt(0)
	s_waitcnt lgkmcnt(0)
	s_barrier
	s_mov_b64 s[2:3], exec
	v_readlane_b32 s6, v234, 18
	v_readlane_b32 s7, v234, 19
	s_and_b64 s[6:7], s[2:3], s[6:7]
	s_xor_b64 s[2:3], s[6:7], s[2:3]
	s_mov_b64 exec, s[6:7]
	s_cbranch_execz .LBB0_972
	v_readlane_b32 s98, v243, 0
	s_mov_b32 s99, 0
	v_mov_b32_e32 v242, 1
	s_mov_b32 s100, 0
	v_lshl_add_u64 v[246:247], v[244:245], 0, s[98:99]
	global_atomic_add v[246:247], v242, off offset:256
	v_readlane_b32 s101, v243, 1
	s_nop 0
	s_cmp_lt_u32 s101, 16
	s_cselect_b32 s101, 0x100, 0
.Lg6_spin:
	global_load_dword v241, v[246:247], off offset:256 sc1
	global_load_dword v240, v[244:245], off offset:516 sc1
	s_waitcnt vmcnt(0)
	v_subrev_u32_e32 v241, 4, v241
	v_subrev_u32_e32 v240, s101, v240
	v_or_b32_e32 v241, v241, v240
	v_cmp_gt_i32_e32 vcc, 0, v241
	s_cbranch_vccz .Lg6_acq
	s_sleep 1
	s_add_u32 s100, s100, 1
	s_cmp_lt_u32 s100, 0x1000
	s_cbranch_scc1 .Lg6_spin

	.amdhsa_kernel _Z10fwd_kernel4Args
		.amdhsa_group_segment_fixed_size 0
		.amdhsa_private_segment_fixed_size 0
		.amdhsa_kernarg_size 432
		.amdhsa_user_sgpr_count 2
		.amdhsa_user_sgpr_dispatch_ptr 0
		.amdhsa_user_sgpr_queue_ptr 0
		.amdhsa_user_sgpr_kernarg_segment_ptr 1
		.amdhsa_user_sgpr_dispatch_id 0
		.amdhsa_user_sgpr_kernarg_preload_length 0
		.amdhsa_user_sgpr_kernarg_preload_offset 0
		.amdhsa_user_sgpr_private_segment_size 0
		.amdhsa_uses_dynamic_stack 0
		.amdhsa_enable_private_segment 0
		.amdhsa_system_sgpr_workgroup_id_x 1
		.amdhsa_system_sgpr_workgroup_id_y 0
		.amdhsa_system_sgpr_workgroup_id_z 0
		.amdhsa_system_sgpr_workgroup_info 0
		.amdhsa_system_vgpr_workitem_id 2
		.amdhsa_next_free_vgpr 248
		.amdhsa_next_free_sgpr 102
		.amdhsa_accum_offset 248
		.amdhsa_reserve_vcc 1
		.amdhsa_float_round_mode_32 0
		.amdhsa_float_round_mode_16_64 0
		.amdhsa_float_denorm_mode_32 3
		.amdhsa_float_denorm_mode_16_64 3
		.amdhsa_dx10_clamp 1
		.amdhsa_ieee_mode 1
		.amdhsa_fp16_overflow 0
		.amdhsa_tg_split 0
		.amdhsa_exception_fp_ieee_invalid_op 0
		.amdhsa_exception_fp_denorm_src 0
		.amdhsa_exception_fp_ieee_div_zero 0
		.amdhsa_exception_fp_ieee_overflow 0
		.amdhsa_exception_fp_ieee_underflow 0
		.amdhsa_exception_fp_ieee_inexact 0
		.amdhsa_exception_int_div_zero 0
	.end_amdhsa_kernel

amdhsa.kernels:
  - .agpr_count:     0
    .args:
      - .offset:         0
        .size:           176
        .value_kind:     by_value
      - .offset:         176
        .size:           4
        .value_kind:     hidden_block_count_x
      - .offset:         180
        .size:           4
        .value_kind:     hidden_block_count_y
      - .offset:         184
        .size:           4
        .value_kind:     hidden_block_count_z
      - .offset:         188
        .size:           2
        .value_kind:     hidden_group_size_x
      - .offset:         190
        .size:           2
        .value_kind:     hidden_group_size_y
      - .offset:         192
        .size:           2
        .value_kind:     hidden_group_size_z
      - .offset:         194
        .size:           2
        .value_kind:     hidden_remainder_x
      - .offset:         196
        .size:           2
        .value_kind:     hidden_remainder_y
      - .offset:         198
        .size:           2
        .value_kind:     hidden_remainder_z
      - .offset:         216
        .size:           8
        .value_kind:     hidden_global_offset_x
      - .offset:         224
        .size:           8
        .value_kind:     hidden_global_offset_y
      - .offset:         232
        .size:           8
        .value_kind:     hidden_global_offset_z
      - .offset:         240
        .size:           2
        .value_kind:     hidden_grid_dims
      - .offset:         264
        .size:           8
        .value_kind:     hidden_multigrid_sync_arg
      - .offset:         296
        .size:           4
        .value_kind:     hidden_dynamic_lds_size
    .group_segment_fixed_size: 0
    .kernarg_segment_align: 8
    .kernarg_segment_size: 432
    .language:       OpenCL C
    .language_version:
      - 2
      - 0
    .max_flat_workgroup_size: 512
    .name:           _Z10fwd_kernel4Args
    .private_segment_fixed_size: 0
    .sgpr_count:     108
    .sgpr_spill_count: 51
    .symbol:         _Z10fwd_kernel4Args.kd
    .uniform_work_group_size: 1
    .uses_dynamic_stack: false
    .vgpr_count:     248
    .vgpr_spill_count: 0
    .wavefront_size: 64
